# GEMM K-loops: one-instruction M0 formation, no-op setprio pairs and repeated lgkmcnt waits dropped, odd-tile staging via instruction offset
# speedup vs baseline: 1.0113x; 1.0056x over previous
; #define PG8_STAGE(bufoff, gbase, voff) do { _Pragma("unroll") for (int _i = 0; _i < 2; ++_i) \
;         __builtin_amdgcn_global_load_lds((const unsigned*)((const char*)(gbase) + (voff)[_i]), (PG8_LAS unsigned*)(lds + (bufoff) + ldsw + _i * 8192), 16, 0, 0); } while (0)
; #define PG8_LDA(dst, b, h) do { _Pragma("unroll") for (int m = 0; m < 4; ++m) _Pragma("unroll") for (int k = 0; k < 2; ++k) dst[m][k] = *(const PG8_LAS bf16x8*)(lds + PG8_SA(b, h) + aoff + m * 2048 + k * 1024); } while (0)
; #define PG8_LDB(dst, b, h) do { _Pragma("unroll") for (int n = 0; n < 2; ++n) _Pragma("unroll") for (int k = 0; k < 2; ++k) dst[n][k] = *(const PG8_LAS bf16x8*)(lds + PG8_SB(b, h) + boff + n * 2048 + k * 1024); } while (0)
; #define PG8_WAIT_V(n) asm volatile("s_waitcnt vmcnt(" #n ")" ::: "memory")
; #define PG8_WAIT_L(n) asm volatile("s_waitcnt lgkmcnt(" #n ")" ::: "memory")
; #define PG8_BAR __builtin_amdgcn_s_barrier()
; #define PG8_SCHED __builtin_amdgcn_sched_barrier(0)
; template <class Epi, class Sched, bool ALIGN_EPI = false, bool SP2 = false>
; __device__ __forceinline__ void gemm_phase(PG8_LAS unsigned char* lds, const Gemm g, const Sched& S, const Epi& E) {
;     ...
;         const bool has_next = S.next(ui + 1, nxt);
;         const char* nA = has_next ? (const char*)g.A + (size_t)nxt.pm * tstep : cA; const char* nB = has_next ? (const char*)g.Bt + (size_t)nxt.pn * tstep : cB;
;         for (int t = 0; t < nt; t += 2) {
;             const bool last = (t == nt - 2);
;             const char* a1 = cA + (size_t)(t + 1) * kstep;
;             const char* a2 = last ? nA : cA + (size_t)(t + 2) * kstep; const char* b2 = last ? nB : cB + (size_t)(t + 2) * kstep;
;             const char* a3 = a2 + kstep; const char* b3 = b2 + kstep;
;             if (last && has_next) S.a_ready(nxt);
;             if constexpr (SP2) {
;             PG8_LDB(B0, 0, 0); PG8_LDB(B1, 0, 1); PG8_SCHED; PG8_LDA(At, 0, 0); PG8_STAGE(PG8_SA(1, 1), a1 + hstep, voffA);
;             PG8_WAIT_V(8); PG8_WAIT_L(0); PG8_BAR; PG8_MMA(0, 0, At, B0); PG8_MMA(0, 1, At, B1); PG8_BAR; PG8_SCHED;
;             PG8_LDA(At, 0, 1); PG8_STAGE(PG8_SB(0, 0), b2, voffB); PG8_STAGE(PG8_SB(0, 1), b2 + hstep, voffB); PG8_STAGE(PG8_SA(0, 0), a2, voffA);
;             PG8_WAIT_V(8); PG8_WAIT_L(0); PG8_BAR; PG8_MMA(1, 0, At, B0); PG8_MMA(1, 1, At, B1); PG8_BAR; PG8_SCHED;
.LBB0_341:
	s_add_i32 s44, s20, 2
	s_add_u32 s45, s16, 0x80
	s_addc_u32 s21, s17, 0
	s_cmp_eq_u32 s70, s20
	s_cselect_b32 s21, s7, s21
	s_cselect_b32 s20, s6, s45
	s_cselect_b32 s47, s57, s39
	s_cselect_b32 s46, s56, s33
	ds_read_b128 v[82:85], v167
	ds_read_b128 v[86:89], v167 offset:1024
	ds_read_b128 v[138:141], v167 offset:2048
	ds_read_b128 v[142:145], v167 offset:3072
	ds_read_b128 v[158:161], v167 offset:16384
	ds_read_b128 v[162:165], v167 offset:17408
	ds_read_b128 v[170:173], v167 offset:18432
	ds_read_b128 v[174:177], v167 offset:19456
	v_lshl_add_u64 v[210:211], s[16:17], 0, v[154:155]
	s_add_i32 m0, s63, 0xc000
	ds_read_b128 v[178:181], v169
	ds_read_b128 v[182:185], v169 offset:1024
	ds_read_b128 v[186:189], v169 offset:2048
	ds_read_b128 v[190:193], v169 offset:3072
	ds_read_b128 v[194:197], v169 offset:4096
	ds_read_b128 v[198:201], v169 offset:5120
	ds_read_b128 v[202:205], v169 offset:6144
	ds_read_b128 v[206:209], v169 offset:7168
	global_load_lds_dwordx4 v[210:211], off
	s_add_i32 m0, s63, 0xe000
	v_lshl_add_u64 v[210:211], s[16:17], 0, v[156:157]
	global_load_lds_dwordx4 v[210:211], off
	s_waitcnt vmcnt(8)
	s_waitcnt lgkmcnt(0)
	s_barrier
	s_setprio 1
	v_mfma_f32_16x16x32_bf16 v[134:137], v[82:85], v[178:181], v[134:137]
	v_mfma_f32_16x16x32_bf16 v[130:133], v[138:141], v[178:181], v[130:133]
	v_mfma_f32_16x16x32_bf16 v[126:129], v[82:85], v[186:189], v[126:129]
	v_mfma_f32_16x16x32_bf16 v[122:125], v[138:141], v[186:189], v[122:125]
	v_mfma_f32_16x16x32_bf16 v[118:121], v[82:85], v[194:197], v[118:121]
	v_mfma_f32_16x16x32_bf16 v[114:117], v[138:141], v[194:197], v[114:117]
	v_mfma_f32_16x16x32_bf16 v[110:113], v[82:85], v[202:205], v[110:113]
	v_mfma_f32_16x16x32_bf16 v[106:109], v[138:141], v[202:205], v[106:109]
	v_mfma_f32_16x16x32_bf16 v[134:137], v[86:89], v[182:185], v[134:137]
	v_mfma_f32_16x16x32_bf16 v[130:133], v[142:145], v[182:185], v[130:133]
	v_mfma_f32_16x16x32_bf16 v[126:129], v[86:89], v[190:193], v[126:129]
	v_mfma_f32_16x16x32_bf16 v[122:125], v[142:145], v[190:193], v[122:125]
	v_mfma_f32_16x16x32_bf16 v[118:121], v[86:89], v[198:201], v[118:121]
	v_mfma_f32_16x16x32_bf16 v[114:117], v[142:145], v[198:201], v[114:117]
	v_mfma_f32_16x16x32_bf16 v[110:113], v[86:89], v[206:209], v[110:113]
	v_mfma_f32_16x16x32_bf16 v[106:109], v[142:145], v[206:209], v[106:109]
	v_mfma_f32_16x16x32_bf16 v[62:65], v[158:161], v[178:181], v[62:65]
	v_mfma_f32_16x16x32_bf16 v[58:61], v[170:173], v[178:181], v[58:61]
	v_mfma_f32_16x16x32_bf16 v[54:57], v[158:161], v[186:189], v[54:57]
	v_mfma_f32_16x16x32_bf16 v[50:53], v[170:173], v[186:189], v[50:53]
	v_mfma_f32_16x16x32_bf16 v[46:49], v[158:161], v[194:197], v[46:49]
	v_mfma_f32_16x16x32_bf16 v[42:45], v[170:173], v[194:197], v[42:45]
	v_mfma_f32_16x16x32_bf16 v[38:41], v[158:161], v[202:205], v[38:41]
	v_mfma_f32_16x16x32_bf16 v[34:37], v[170:173], v[202:205], v[34:37]
	v_mfma_f32_16x16x32_bf16 v[62:65], v[162:165], v[182:185], v[62:65]
	v_mfma_f32_16x16x32_bf16 v[58:61], v[174:177], v[182:185], v[58:61]
	v_mfma_f32_16x16x32_bf16 v[54:57], v[162:165], v[190:193], v[54:57]
	v_mfma_f32_16x16x32_bf16 v[50:53], v[174:177], v[190:193], v[50:53]
	v_mfma_f32_16x16x32_bf16 v[46:49], v[162:165], v[198:201], v[46:49]
	v_mfma_f32_16x16x32_bf16 v[42:45], v[174:177], v[198:201], v[42:45]
	v_mfma_f32_16x16x32_bf16 v[38:41], v[162:165], v[206:209], v[38:41]
	v_mfma_f32_16x16x32_bf16 v[34:37], v[174:177], v[206:209], v[34:37]
	s_setprio 0
	s_barrier
	v_lshl_add_u64 v[210:211], s[46:47], 0, v[148:149]
	s_add_i32 m0, s62, 0x10000
	ds_read_b128 v[178:181], v169 offset:16384
	ds_read_b128 v[182:185], v169 offset:17408
	ds_read_b128 v[186:189], v169 offset:18432
	ds_read_b128 v[190:193], v169 offset:19456
	ds_read_b128 v[194:197], v169 offset:20480
	ds_read_b128 v[198:201], v169 offset:21504
	ds_read_b128 v[202:205], v169 offset:22528
	ds_read_b128 v[206:209], v169 offset:23552
	global_load_lds_dwordx4 v[210:211], off
	s_add_i32 m0, s62, 0x12000
	v_lshl_add_u64 v[212:213], s[46:47], 0, v[152:153]
	s_add_u32 s46, s46, s10
	s_addc_u32 s47, s47, s11
	global_load_lds_dwordx4 v[212:213], off
	v_lshl_add_u64 v[214:215], s[46:47], 0, v[148:149]
	s_add_i32 m0, s62, 0x14000
	v_lshl_add_u64 v[218:219], s[46:47], 0, v[152:153]
	global_load_lds_dwordx4 v[214:215], off
	s_add_i32 m0, s62, 0x16000
	v_lshl_add_u64 v[220:221], s[20:21], 0, v[146:147]
	global_load_lds_dwordx4 v[218:219], off
	s_mov_b32 m0, s63
	v_lshl_add_u64 v[222:223], s[20:21], 0, v[150:151]
	global_load_lds_dwordx4 v[220:221], off
	s_mov_b32 m0, s64
	s_nop 0
	global_load_lds_dwordx4 v[222:223], off
	s_waitcnt vmcnt(8)
	s_waitcnt lgkmcnt(0)
	s_barrier
; #define PG8_STAGE(bufoff, gbase, voff) do { _Pragma("unroll") for (int _i = 0; _i < 2; ++_i) \
;         __builtin_amdgcn_global_load_lds((const unsigned*)((const char*)(gbase) + (voff)[_i]), (PG8_LAS unsigned*)(lds + (bufoff) + ldsw + _i * 8192), 16, 0, 0); } while (0)
; #define PG8_LDA(dst, b, h) do { _Pragma("unroll") for (int m = 0; m < 4; ++m) _Pragma("unroll") for (int k = 0; k < 2; ++k) dst[m][k] = *(const PG8_LAS bf16x8*)(lds + PG8_SA(b, h) + aoff + m * 2048 + k * 1024); } while (0)
; #define PG8_LDB(dst, b, h) do { _Pragma("unroll") for (int n = 0; n < 2; ++n) _Pragma("unroll") for (int k = 0; k < 2; ++k) dst[n][k] = *(const PG8_LAS bf16x8*)(lds + PG8_SB(b, h) + boff + n * 2048 + k * 1024); } while (0)
; #define PG8_MMA(ai, bj, At, Bt) do { __builtin_amdgcn_s_setprio(1); _Pragma("unroll") for (int m = 0; m < 4; ++m) _Pragma("unroll") for (int n = 0; n < 2; ++n) _Pragma("unroll") for (int k = 0; k < 2; ++k) \
;         acc[ai][bj][m][n] = __builtin_amdgcn_mfma_f32_16x16x32_bf16(Bt[n][k], At[m][k], acc[ai][bj][m][n], 0, 0, 0); __builtin_amdgcn_s_setprio(0); } while (0)
; #define PG8_WAIT_V(n) asm volatile("s_waitcnt vmcnt(" #n ")" ::: "memory")
; #define PG8_WAIT_L(n) asm volatile("s_waitcnt lgkmcnt(" #n ")" ::: "memory")
; #define PG8_BAR __builtin_amdgcn_s_barrier()
; #define PG8_SCHED __builtin_amdgcn_sched_barrier(0)
; template <class Epi, class Sched, bool ALIGN_EPI = false, bool SP2 = false>
; __device__ __forceinline__ void gemm_phase(PG8_LAS unsigned char* lds, const Gemm g, const Sched& S, const Epi& E) {
;     ...
;             PG8_WAIT_V(8); PG8_WAIT_L(0); PG8_BAR; PG8_MMA(1, 0, At, B0); PG8_MMA(1, 1, At, B1); PG8_BAR; PG8_SCHED;
;             PG8_LDB(B0, 1, 0); PG8_LDB(B1, 1, 1); PG8_SCHED; PG8_LDA(At, 1, 0); PG8_STAGE(PG8_SA(0, 1), a2 + hstep, voffA);
;             PG8_WAIT_V(8); PG8_WAIT_L(0); PG8_BAR; PG8_MMA(0, 0, At, B0); PG8_MMA(0, 1, At, B1); PG8_BAR; PG8_SCHED;
	s_setprio 1
	v_mfma_f32_16x16x32_bf16 v[102:105], v[82:85], v[178:181], v[102:105]
	v_mfma_f32_16x16x32_bf16 v[98:101], v[138:141], v[178:181], v[98:101]
	v_mfma_f32_16x16x32_bf16 v[94:97], v[82:85], v[186:189], v[94:97]
	v_mfma_f32_16x16x32_bf16 v[90:93], v[138:141], v[186:189], v[90:93]
	v_mfma_f32_16x16x32_bf16 v[78:81], v[82:85], v[194:197], v[78:81]
	v_mfma_f32_16x16x32_bf16 v[74:77], v[138:141], v[194:197], v[74:77]
	v_mfma_f32_16x16x32_bf16 v[70:73], v[82:85], v[202:205], v[70:73]
	v_mfma_f32_16x16x32_bf16 v[66:69], v[138:141], v[202:205], v[66:69]
	v_mfma_f32_16x16x32_bf16 v[102:105], v[86:89], v[182:185], v[102:105]
	v_mfma_f32_16x16x32_bf16 v[98:101], v[142:145], v[182:185], v[98:101]
	v_mfma_f32_16x16x32_bf16 v[94:97], v[86:89], v[190:193], v[94:97]
	v_mfma_f32_16x16x32_bf16 v[90:93], v[142:145], v[190:193], v[90:93]
	v_mfma_f32_16x16x32_bf16 v[78:81], v[86:89], v[198:201], v[78:81]
	v_mfma_f32_16x16x32_bf16 v[74:77], v[142:145], v[198:201], v[74:77]
	v_mfma_f32_16x16x32_bf16 v[70:73], v[86:89], v[206:209], v[70:73]
	v_mfma_f32_16x16x32_bf16 v[66:69], v[142:145], v[206:209], v[66:69]
	v_mfma_f32_16x16x32_bf16 v[30:33], v[158:161], v[178:181], v[30:33]
	v_mfma_f32_16x16x32_bf16 v[26:29], v[170:173], v[178:181], v[26:29]
	v_mfma_f32_16x16x32_bf16 v[22:25], v[158:161], v[186:189], v[22:25]
	v_mfma_f32_16x16x32_bf16 v[18:21], v[170:173], v[186:189], v[18:21]
	v_mfma_f32_16x16x32_bf16 v[14:17], v[158:161], v[194:197], v[14:17]
	v_mfma_f32_16x16x32_bf16 v[10:13], v[170:173], v[194:197], v[10:13]
	v_mfma_f32_16x16x32_bf16 v[6:9], v[158:161], v[202:205], v[6:9]
	v_mfma_f32_16x16x32_bf16 v[2:5], v[170:173], v[202:205], v[2:5]
	v_mfma_f32_16x16x32_bf16 v[30:33], v[162:165], v[182:185], v[30:33]
	v_mfma_f32_16x16x32_bf16 v[26:29], v[174:177], v[182:185], v[26:29]
	v_mfma_f32_16x16x32_bf16 v[22:25], v[162:165], v[190:193], v[22:25]
	v_mfma_f32_16x16x32_bf16 v[18:21], v[174:177], v[190:193], v[18:21]
	v_mfma_f32_16x16x32_bf16 v[14:17], v[162:165], v[198:201], v[14:17]
	v_mfma_f32_16x16x32_bf16 v[10:13], v[174:177], v[198:201], v[10:13]
	v_mfma_f32_16x16x32_bf16 v[6:9], v[162:165], v[206:209], v[6:9]
	v_mfma_f32_16x16x32_bf16 v[2:5], v[174:177], v[206:209], v[2:5]
	s_setprio 0
	s_barrier
	ds_read_b128 v[82:85], v167 offset:32768
	ds_read_b128 v[86:89], v167 offset:33792
	ds_read_b128 v[138:141], v167 offset:34816
	ds_read_b128 v[142:145], v167 offset:35840
	ds_read_b128 v[158:161], v167 offset:49152
	ds_read_b128 v[162:165], v167 offset:50176
	ds_read_b128 v[170:173], v167 offset:51200
	ds_read_b128 v[174:177], v167 offset:52224
	s_add_u32 s20, s20, s10
	s_addc_u32 s21, s21, s11
	s_mov_b32 m0, s65
	v_lshl_add_u64 v[224:225], s[20:21], 0, v[146:147]
	ds_read_b128 v[178:181], v169 offset:32768
	ds_read_b128 v[182:185], v169 offset:33792
	ds_read_b128 v[186:189], v169 offset:34816
	ds_read_b128 v[190:193], v169 offset:35840
	ds_read_b128 v[194:197], v169 offset:36864
	ds_read_b128 v[198:201], v169 offset:37888
	ds_read_b128 v[202:205], v169 offset:38912
	ds_read_b128 v[206:209], v169 offset:39936
	global_load_lds_dwordx4 v[224:225], off
	s_mov_b32 m0, s66
	v_lshl_add_u64 v[224:225], s[20:21], 0, v[150:151]
	global_load_lds_dwordx4 v[224:225], off
	s_waitcnt vmcnt(8)
	s_waitcnt lgkmcnt(0)
	s_barrier
	s_setprio 1
	v_mfma_f32_16x16x32_bf16 v[134:137], v[82:85], v[178:181], v[134:137]
	v_mfma_f32_16x16x32_bf16 v[130:133], v[138:141], v[178:181], v[130:133]
	v_mfma_f32_16x16x32_bf16 v[126:129], v[82:85], v[186:189], v[126:129]
	v_mfma_f32_16x16x32_bf16 v[122:125], v[138:141], v[186:189], v[122:125]
	v_mfma_f32_16x16x32_bf16 v[118:121], v[82:85], v[194:197], v[118:121]
	v_mfma_f32_16x16x32_bf16 v[114:117], v[138:141], v[194:197], v[114:117]
	v_mfma_f32_16x16x32_bf16 v[110:113], v[82:85], v[202:205], v[110:113]
	v_mfma_f32_16x16x32_bf16 v[106:109], v[138:141], v[202:205], v[106:109]
	v_mfma_f32_16x16x32_bf16 v[134:137], v[86:89], v[182:185], v[134:137]
	v_mfma_f32_16x16x32_bf16 v[130:133], v[142:145], v[182:185], v[130:133]
	v_mfma_f32_16x16x32_bf16 v[126:129], v[86:89], v[190:193], v[126:129]
	v_mfma_f32_16x16x32_bf16 v[122:125], v[142:145], v[190:193], v[122:125]
	v_mfma_f32_16x16x32_bf16 v[118:121], v[86:89], v[198:201], v[118:121]
	v_mfma_f32_16x16x32_bf16 v[114:117], v[142:145], v[198:201], v[114:117]
	v_mfma_f32_16x16x32_bf16 v[110:113], v[86:89], v[206:209], v[110:113]
	v_mfma_f32_16x16x32_bf16 v[106:109], v[142:145], v[206:209], v[106:109]
	v_mfma_f32_16x16x32_bf16 v[62:65], v[158:161], v[178:181], v[62:65]
	v_mfma_f32_16x16x32_bf16 v[58:61], v[170:173], v[178:181], v[58:61]
	v_mfma_f32_16x16x32_bf16 v[54:57], v[158:161], v[186:189], v[54:57]
	v_mfma_f32_16x16x32_bf16 v[50:53], v[170:173], v[186:189], v[50:53]
	v_mfma_f32_16x16x32_bf16 v[46:49], v[158:161], v[194:197], v[46:49]
	v_mfma_f32_16x16x32_bf16 v[42:45], v[170:173], v[194:197], v[42:45]
	v_mfma_f32_16x16x32_bf16 v[38:41], v[158:161], v[202:205], v[38:41]
	v_mfma_f32_16x16x32_bf16 v[34:37], v[170:173], v[202:205], v[34:37]
	v_mfma_f32_16x16x32_bf16 v[62:65], v[162:165], v[182:185], v[62:65]
	v_mfma_f32_16x16x32_bf16 v[58:61], v[174:177], v[182:185], v[58:61]
	v_mfma_f32_16x16x32_bf16 v[54:57], v[162:165], v[190:193], v[54:57]
	v_mfma_f32_16x16x32_bf16 v[50:53], v[174:177], v[190:193], v[50:53]
	v_mfma_f32_16x16x32_bf16 v[46:49], v[162:165], v[198:201], v[46:49]
	v_mfma_f32_16x16x32_bf16 v[42:45], v[174:177], v[198:201], v[42:45]
	v_mfma_f32_16x16x32_bf16 v[38:41], v[162:165], v[206:209], v[38:41]
	v_mfma_f32_16x16x32_bf16 v[34:37], v[174:177], v[206:209], v[34:37]
	s_setprio 0
	s_barrier
; #define PG8_STAGE(bufoff, gbase, voff) do { _Pragma("unroll") for (int _i = 0; _i < 2; ++_i) \
;         __builtin_amdgcn_global_load_lds((const unsigned*)((const char*)(gbase) + (voff)[_i]), (PG8_LAS unsigned*)(lds + (bufoff) + ldsw + _i * 8192), 16, 0, 0); } while (0)
; #define PG8_LDA(dst, b, h) do { _Pragma("unroll") for (int m = 0; m < 4; ++m) _Pragma("unroll") for (int k = 0; k < 2; ++k) dst[m][k] = *(const PG8_LAS bf16x8*)(lds + PG8_SA(b, h) + aoff + m * 2048 + k * 1024); } while (0)
; #define PG8_MMA(ai, bj, At, Bt) do { __builtin_amdgcn_s_setprio(1); _Pragma("unroll") for (int m = 0; m < 4; ++m) _Pragma("unroll") for (int n = 0; n < 2; ++n) _Pragma("unroll") for (int k = 0; k < 2; ++k) \
;         acc[ai][bj][m][n] = __builtin_amdgcn_mfma_f32_16x16x32_bf16(Bt[n][k], At[m][k], acc[ai][bj][m][n], 0, 0, 0); __builtin_amdgcn_s_setprio(0); } while (0)
; #define PG8_WAIT_V(n) asm volatile("s_waitcnt vmcnt(" #n ")" ::: "memory")
; #define PG8_WAIT_L(n) asm volatile("s_waitcnt lgkmcnt(" #n ")" ::: "memory")
; #define PG8_BAR __builtin_amdgcn_s_barrier()
; #define PG8_SCHED __builtin_amdgcn_sched_barrier(0)
; template <class Epi, class Sched, bool ALIGN_EPI = false, bool SP2 = false>
; __device__ __forceinline__ void gemm_phase(PG8_LAS unsigned char* lds, const Gemm g, const Sched& S, const Epi& E) {
;     ...
;         for (int t = 0; t < nt; t += 2) {
;             const bool last = (t == nt - 2);
;             const char* a1 = cA + (size_t)(t + 1) * kstep;
;             const char* a2 = last ? nA : cA + (size_t)(t + 2) * kstep; const char* b2 = last ? nB : cB + (size_t)(t + 2) * kstep;
;             const char* a3 = a2 + kstep; const char* b3 = b2 + kstep;
;     ...
;             PG8_LDA(At, 1, 1); PG8_STAGE(PG8_SB(1, 0), b3, voffB); PG8_STAGE(PG8_SB(1, 1), b3 + hstep, voffB); PG8_STAGE(PG8_SA(1, 0), a3, voffA);
;             PG8_WAIT_V(8); PG8_WAIT_L(0); PG8_BAR; PG8_MMA(1, 0, At, B0); PG8_MMA(1, 1, At, B1); PG8_BAR; PG8_SCHED;
	s_add_i32 m0, s62, 0x17f80
	ds_read_b128 v[178:181], v169 offset:49152
	ds_read_b128 v[182:185], v169 offset:50176
	ds_read_b128 v[186:189], v169 offset:51200
	global_load_lds_dwordx4 v[210:211], off offset:128
	s_add_i32 m0, s62, 0x19f80
	ds_read_b128 v[190:193], v169 offset:52224
	global_load_lds_dwordx4 v[212:213], off offset:128
	s_add_i32 m0, s62, 0x1bf80
	ds_read_b128 v[194:197], v169 offset:53248
	global_load_lds_dwordx4 v[214:215], off offset:128
	s_add_i32 m0, s62, 0x1df80
	ds_read_b128 v[198:201], v169 offset:54272
	global_load_lds_dwordx4 v[218:219], off offset:128
	s_sub_i32 m0, s68, 0x80
	ds_read_b128 v[202:205], v169 offset:55296
	global_load_lds_dwordx4 v[220:221], off offset:128
	s_sub_i32 m0, s69, 0x80
	ds_read_b128 v[206:209], v169 offset:56320
	global_load_lds_dwordx4 v[222:223], off offset:128
	s_waitcnt vmcnt(8)
	s_waitcnt lgkmcnt(0)
	s_barrier
	s_setprio 1
	v_mfma_f32_16x16x32_bf16 v[102:105], v[82:85], v[178:181], v[102:105]
	v_mfma_f32_16x16x32_bf16 v[98:101], v[138:141], v[178:181], v[98:101]
	v_mfma_f32_16x16x32_bf16 v[94:97], v[82:85], v[186:189], v[94:97]
	v_mfma_f32_16x16x32_bf16 v[90:93], v[138:141], v[186:189], v[90:93]
	v_mfma_f32_16x16x32_bf16 v[78:81], v[82:85], v[194:197], v[78:81]
	v_mfma_f32_16x16x32_bf16 v[74:77], v[138:141], v[194:197], v[74:77]
	v_mfma_f32_16x16x32_bf16 v[70:73], v[82:85], v[202:205], v[70:73]
	v_mfma_f32_16x16x32_bf16 v[66:69], v[138:141], v[202:205], v[66:69]
	v_mfma_f32_16x16x32_bf16 v[102:105], v[86:89], v[182:185], v[102:105]
	v_mfma_f32_16x16x32_bf16 v[98:101], v[142:145], v[182:185], v[98:101]
	v_mfma_f32_16x16x32_bf16 v[94:97], v[86:89], v[190:193], v[94:97]
	v_mfma_f32_16x16x32_bf16 v[90:93], v[142:145], v[190:193], v[90:93]
	v_mfma_f32_16x16x32_bf16 v[78:81], v[86:89], v[198:201], v[78:81]
	v_mfma_f32_16x16x32_bf16 v[74:77], v[142:145], v[198:201], v[74:77]
	v_mfma_f32_16x16x32_bf16 v[70:73], v[86:89], v[206:209], v[70:73]
	v_mfma_f32_16x16x32_bf16 v[66:69], v[142:145], v[206:209], v[66:69]
	v_mfma_f32_16x16x32_bf16 v[30:33], v[158:161], v[178:181], v[30:33]
	v_mfma_f32_16x16x32_bf16 v[26:29], v[170:173], v[178:181], v[26:29]
	v_mfma_f32_16x16x32_bf16 v[22:25], v[158:161], v[186:189], v[22:25]
	v_mfma_f32_16x16x32_bf16 v[18:21], v[170:173], v[186:189], v[18:21]
	v_mfma_f32_16x16x32_bf16 v[14:17], v[158:161], v[194:197], v[14:17]
	v_mfma_f32_16x16x32_bf16 v[10:13], v[170:173], v[194:197], v[10:13]
	v_mfma_f32_16x16x32_bf16 v[6:9], v[158:161], v[202:205], v[6:9]
	v_mfma_f32_16x16x32_bf16 v[2:5], v[170:173], v[202:205], v[2:5]
	v_mfma_f32_16x16x32_bf16 v[30:33], v[162:165], v[182:185], v[30:33]
	v_mfma_f32_16x16x32_bf16 v[26:29], v[174:177], v[182:185], v[26:29]
	v_mfma_f32_16x16x32_bf16 v[22:25], v[162:165], v[190:193], v[22:25]
	v_mfma_f32_16x16x32_bf16 v[18:21], v[174:177], v[190:193], v[18:21]
	v_mfma_f32_16x16x32_bf16 v[14:17], v[162:165], v[198:201], v[14:17]
	v_mfma_f32_16x16x32_bf16 v[10:13], v[174:177], v[198:201], v[10:13]
	v_mfma_f32_16x16x32_bf16 v[6:9], v[162:165], v[206:209], v[6:9]
	v_mfma_f32_16x16x32_bf16 v[2:5], v[174:177], v[206:209], v[2:5]
	s_setprio 0
	s_barrier
	s_add_u32 s16, s16, 0x100
	s_addc_u32 s17, s17, 0
	s_add_u32 s33, s33, 0x100
	s_addc_u32 s39, s39, 0
	s_cmp_ge_i32 s44, s67
	s_mov_b32 s20, s44
	s_cbranch_scc0 .LBB0_341
	s_movk_i32 s39, 0x5000

; #define PG8_STAGE(bufoff, gbase, voff) do { _Pragma("unroll") for (int _i = 0; _i < 2; ++_i) \
;         __builtin_amdgcn_global_load_lds((const unsigned*)((const char*)(gbase) + (voff)[_i]), (PG8_LAS unsigned*)(lds + (bufoff) + ldsw + _i * 8192), 16, 0, 0); } while (0)
; #define PG8_LDA(dst, b, h) do { _Pragma("unroll") for (int m = 0; m < 4; ++m) _Pragma("unroll") for (int k = 0; k < 2; ++k) dst[m][k] = *(const PG8_LAS bf16x8*)(lds + PG8_SA(b, h) + aoff + m * 2048 + k * 1024); } while (0)
; #define PG8_LDB(dst, b, h) do { _Pragma("unroll") for (int n = 0; n < 2; ++n) _Pragma("unroll") for (int k = 0; k < 2; ++k) dst[n][k] = *(const PG8_LAS bf16x8*)(lds + PG8_SB(b, h) + boff + n * 2048 + k * 1024); } while (0)
; #define PG8_WAIT_V(n) asm volatile("s_waitcnt vmcnt(" #n ")" ::: "memory")
; #define PG8_WAIT_L(n) asm volatile("s_waitcnt lgkmcnt(" #n ")" ::: "memory")
; #define PG8_BAR __builtin_amdgcn_s_barrier()
; #define PG8_SCHED __builtin_amdgcn_sched_barrier(0)
; template <class Epi, class Sched, bool ALIGN_EPI = false, bool SP2 = false>
; __device__ __forceinline__ void gemm_phase(PG8_LAS unsigned char* lds, const Gemm g, const Sched& S, const Epi& E) {
;     ...
;         const bool has_next = S.next(ui + 1, nxt);
;         const char* nA = has_next ? (const char*)g.A + (size_t)nxt.pm * tstep : cA; const char* nB = has_next ? (const char*)g.Bt + (size_t)nxt.pn * tstep : cB;
;         for (int t = 0; t < nt; t += 2) {
;             const bool last = (t == nt - 2);
;             const char* a1 = cA + (size_t)(t + 1) * kstep;
;             const char* a2 = last ? nA : cA + (size_t)(t + 2) * kstep; const char* b2 = last ? nB : cB + (size_t)(t + 2) * kstep;
;             const char* a3 = a2 + kstep; const char* b3 = b2 + kstep;
;             if (last && has_next) S.a_ready(nxt);
;             if constexpr (SP2) {
;             PG8_LDB(B0, 0, 0); PG8_LDB(B1, 0, 1); PG8_SCHED; PG8_LDA(At, 0, 0); PG8_STAGE(PG8_SA(1, 1), a1 + hstep, voffA);
;             PG8_WAIT_V(8); PG8_WAIT_L(0); PG8_BAR; PG8_MMA(0, 0, At, B0); PG8_MMA(0, 1, At, B1); PG8_BAR; PG8_SCHED;
;             PG8_LDA(At, 0, 1); PG8_STAGE(PG8_SB(0, 0), b2, voffB); PG8_STAGE(PG8_SB(0, 1), b2 + hstep, voffB); PG8_STAGE(PG8_SA(0, 0), a2, voffA);
;             PG8_WAIT_V(8); PG8_WAIT_L(0); PG8_BAR; PG8_MMA(1, 0, At, B0); PG8_MMA(1, 1, At, B1); PG8_BAR; PG8_SCHED;
.LBB0_520:
	s_add_i32 s69, s20, 2
	s_add_u32 s70, s8, 0x80
	s_addc_u32 s21, s9, 0
	s_cmp_eq_u32 s63, s20
	s_cselect_b32 s21, s49, s21
	s_cselect_b32 s20, s48, s70
	s_cselect_b32 s71, s51, s53
	s_cselect_b32 s70, s50, s52
	ds_read_b128 v[130:133], v185
	ds_read_b128 v[134:137], v185 offset:1024
	ds_read_b128 v[138:141], v185 offset:2048
	ds_read_b128 v[142:145], v185 offset:3072
	ds_read_b128 v[146:149], v185 offset:16384
	ds_read_b128 v[150:153], v185 offset:17408
	ds_read_b128 v[166:169], v185 offset:18432
	ds_read_b128 v[170:173], v185 offset:19456
	v_lshl_add_u64 v[186:187], s[8:9], 0, v[162:163]
	s_add_i32 m0, s56, 0xc000
	ds_read_b128 v[174:177], v189
	ds_read_b128 v[178:181], v189 offset:1024
	ds_read_b128 v[190:193], v189 offset:2048
	ds_read_b128 v[194:197], v189 offset:3072
	ds_read_b128 v[198:201], v189 offset:4096
	ds_read_b128 v[202:205], v189 offset:5120
	ds_read_b128 v[206:209], v189 offset:6144
	ds_read_b128 v[210:213], v189 offset:7168
	global_load_lds_dwordx4 v[186:187], off
	s_add_i32 m0, s56, 0xe000
	v_lshl_add_u64 v[186:187], s[8:9], 0, v[164:165]
	global_load_lds_dwordx4 v[186:187], off
	s_waitcnt vmcnt(8)
	s_waitcnt lgkmcnt(0)
	s_barrier
	s_setprio 1
	v_mfma_f32_16x16x32_bf16 v[126:129], v[130:133], v[174:177], v[126:129]
	v_mfma_f32_16x16x32_bf16 v[122:125], v[138:141], v[174:177], v[122:125]
	v_mfma_f32_16x16x32_bf16 v[110:113], v[130:133], v[190:193], v[110:113]
	v_mfma_f32_16x16x32_bf16 v[106:109], v[138:141], v[190:193], v[106:109]
	v_mfma_f32_16x16x32_bf16 v[94:97], v[130:133], v[198:201], v[94:97]
	v_mfma_f32_16x16x32_bf16 v[90:93], v[138:141], v[198:201], v[90:93]
	v_mfma_f32_16x16x32_bf16 v[78:81], v[130:133], v[206:209], v[78:81]
	v_mfma_f32_16x16x32_bf16 v[74:77], v[138:141], v[206:209], v[74:77]
	v_mfma_f32_16x16x32_bf16 v[126:129], v[134:137], v[178:181], v[126:129]
	v_mfma_f32_16x16x32_bf16 v[122:125], v[142:145], v[178:181], v[122:125]
	v_mfma_f32_16x16x32_bf16 v[110:113], v[134:137], v[194:197], v[110:113]
	v_mfma_f32_16x16x32_bf16 v[106:109], v[142:145], v[194:197], v[106:109]
	v_mfma_f32_16x16x32_bf16 v[94:97], v[134:137], v[202:205], v[94:97]
	v_mfma_f32_16x16x32_bf16 v[90:93], v[142:145], v[202:205], v[90:93]
	v_mfma_f32_16x16x32_bf16 v[78:81], v[134:137], v[210:213], v[78:81]
	v_mfma_f32_16x16x32_bf16 v[74:77], v[142:145], v[210:213], v[74:77]
	v_mfma_f32_16x16x32_bf16 v[118:121], v[146:149], v[174:177], v[118:121]
	v_mfma_f32_16x16x32_bf16 v[114:117], v[166:169], v[174:177], v[114:117]
	v_mfma_f32_16x16x32_bf16 v[102:105], v[146:149], v[190:193], v[102:105]
	v_mfma_f32_16x16x32_bf16 v[98:101], v[166:169], v[190:193], v[98:101]
	v_mfma_f32_16x16x32_bf16 v[86:89], v[146:149], v[198:201], v[86:89]
	v_mfma_f32_16x16x32_bf16 v[82:85], v[166:169], v[198:201], v[82:85]
	v_mfma_f32_16x16x32_bf16 v[70:73], v[146:149], v[206:209], v[70:73]
	v_mfma_f32_16x16x32_bf16 v[66:69], v[166:169], v[206:209], v[66:69]
	v_mfma_f32_16x16x32_bf16 v[118:121], v[150:153], v[178:181], v[118:121]
	v_mfma_f32_16x16x32_bf16 v[114:117], v[170:173], v[178:181], v[114:117]
	v_mfma_f32_16x16x32_bf16 v[102:105], v[150:153], v[194:197], v[102:105]
	v_mfma_f32_16x16x32_bf16 v[98:101], v[170:173], v[194:197], v[98:101]
	v_mfma_f32_16x16x32_bf16 v[86:89], v[150:153], v[202:205], v[86:89]
	v_mfma_f32_16x16x32_bf16 v[82:85], v[170:173], v[202:205], v[82:85]
	v_mfma_f32_16x16x32_bf16 v[70:73], v[150:153], v[210:213], v[70:73]
	v_mfma_f32_16x16x32_bf16 v[66:69], v[170:173], v[210:213], v[66:69]
	s_setprio 0
	s_barrier
	v_lshl_add_u64 v[186:187], s[70:71], 0, v[0:1]
	s_add_i32 m0, s30, 0x10000
	ds_read_b128 v[174:177], v189 offset:16384
	ds_read_b128 v[178:181], v189 offset:17408
	ds_read_b128 v[190:193], v189 offset:18432
	ds_read_b128 v[194:197], v189 offset:19456
	ds_read_b128 v[198:201], v189 offset:20480
	ds_read_b128 v[202:205], v189 offset:21504
	ds_read_b128 v[206:209], v189 offset:22528
	ds_read_b128 v[210:213], v189 offset:23552
	global_load_lds_dwordx4 v[186:187], off
	s_add_i32 m0, s30, 0x12000
	v_lshl_add_u64 v[214:215], s[70:71], 0, v[154:155]
	s_add_u32 s70, s70, s12
	s_addc_u32 s71, s71, s13
	global_load_lds_dwordx4 v[214:215], off
	v_lshl_add_u64 v[218:219], s[70:71], 0, v[0:1]
	s_add_i32 m0, s30, 0x14000
	v_lshl_add_u64 v[220:221], s[70:71], 0, v[154:155]
	global_load_lds_dwordx4 v[218:219], off
	s_add_i32 m0, s30, 0x16000
	v_lshl_add_u64 v[222:223], s[20:21], 0, v[158:159]
	global_load_lds_dwordx4 v[220:221], off
	s_mov_b32 m0, s56
	v_lshl_add_u64 v[224:225], s[20:21], 0, v[156:157]
	global_load_lds_dwordx4 v[222:223], off
	s_mov_b32 m0, s57
	s_nop 0
	global_load_lds_dwordx4 v[224:225], off
	s_waitcnt vmcnt(8)
	s_waitcnt lgkmcnt(0)
	s_barrier
; #define PG8_STAGE(bufoff, gbase, voff) do { _Pragma("unroll") for (int _i = 0; _i < 2; ++_i) \
;         __builtin_amdgcn_global_load_lds((const unsigned*)((const char*)(gbase) + (voff)[_i]), (PG8_LAS unsigned*)(lds + (bufoff) + ldsw + _i * 8192), 16, 0, 0); } while (0)
; #define PG8_LDA(dst, b, h) do { _Pragma("unroll") for (int m = 0; m < 4; ++m) _Pragma("unroll") for (int k = 0; k < 2; ++k) dst[m][k] = *(const PG8_LAS bf16x8*)(lds + PG8_SA(b, h) + aoff + m * 2048 + k * 1024); } while (0)
; #define PG8_LDB(dst, b, h) do { _Pragma("unroll") for (int n = 0; n < 2; ++n) _Pragma("unroll") for (int k = 0; k < 2; ++k) dst[n][k] = *(const PG8_LAS bf16x8*)(lds + PG8_SB(b, h) + boff + n * 2048 + k * 1024); } while (0)
; #define PG8_MMA(ai, bj, At, Bt) do { __builtin_amdgcn_s_setprio(1); _Pragma("unroll") for (int m = 0; m < 4; ++m) _Pragma("unroll") for (int n = 0; n < 2; ++n) _Pragma("unroll") for (int k = 0; k < 2; ++k) \
;         acc[ai][bj][m][n] = __builtin_amdgcn_mfma_f32_16x16x32_bf16(Bt[n][k], At[m][k], acc[ai][bj][m][n], 0, 0, 0); __builtin_amdgcn_s_setprio(0); } while (0)
; #define PG8_WAIT_V(n) asm volatile("s_waitcnt vmcnt(" #n ")" ::: "memory")
; #define PG8_WAIT_L(n) asm volatile("s_waitcnt lgkmcnt(" #n ")" ::: "memory")
; #define PG8_BAR __builtin_amdgcn_s_barrier()
; #define PG8_SCHED __builtin_amdgcn_sched_barrier(0)
; template <class Epi, class Sched, bool ALIGN_EPI = false, bool SP2 = false>
; __device__ __forceinline__ void gemm_phase(PG8_LAS unsigned char* lds, const Gemm g, const Sched& S, const Epi& E) {
;     ...
;             PG8_WAIT_V(8); PG8_WAIT_L(0); PG8_BAR; PG8_MMA(1, 0, At, B0); PG8_MMA(1, 1, At, B1); PG8_BAR; PG8_SCHED;
;             PG8_LDB(B0, 1, 0); PG8_LDB(B1, 1, 1); PG8_SCHED; PG8_LDA(At, 1, 0); PG8_STAGE(PG8_SA(0, 1), a2 + hstep, voffA);
;             PG8_WAIT_V(8); PG8_WAIT_L(0); PG8_BAR; PG8_MMA(0, 0, At, B0); PG8_MMA(0, 1, At, B1); PG8_BAR; PG8_SCHED;
	s_setprio 1
	v_mfma_f32_16x16x32_bf16 v[62:65], v[130:133], v[174:177], v[62:65]
	v_mfma_f32_16x16x32_bf16 v[58:61], v[138:141], v[174:177], v[58:61]
	v_mfma_f32_16x16x32_bf16 v[46:49], v[130:133], v[190:193], v[46:49]
	v_mfma_f32_16x16x32_bf16 v[42:45], v[138:141], v[190:193], v[42:45]
	v_mfma_f32_16x16x32_bf16 v[30:33], v[130:133], v[198:201], v[30:33]
	v_mfma_f32_16x16x32_bf16 v[26:29], v[138:141], v[198:201], v[26:29]
	v_mfma_f32_16x16x32_bf16 v[14:17], v[130:133], v[206:209], v[14:17]
	v_mfma_f32_16x16x32_bf16 v[10:13], v[138:141], v[206:209], v[10:13]
	v_mfma_f32_16x16x32_bf16 v[62:65], v[134:137], v[178:181], v[62:65]
	v_mfma_f32_16x16x32_bf16 v[58:61], v[142:145], v[178:181], v[58:61]
	v_mfma_f32_16x16x32_bf16 v[46:49], v[134:137], v[194:197], v[46:49]
	v_mfma_f32_16x16x32_bf16 v[42:45], v[142:145], v[194:197], v[42:45]
	v_mfma_f32_16x16x32_bf16 v[30:33], v[134:137], v[202:205], v[30:33]
	v_mfma_f32_16x16x32_bf16 v[26:29], v[142:145], v[202:205], v[26:29]
	v_mfma_f32_16x16x32_bf16 v[14:17], v[134:137], v[210:213], v[14:17]
	v_mfma_f32_16x16x32_bf16 v[10:13], v[142:145], v[210:213], v[10:13]
	v_mfma_f32_16x16x32_bf16 v[54:57], v[146:149], v[174:177], v[54:57]
	v_mfma_f32_16x16x32_bf16 v[50:53], v[166:169], v[174:177], v[50:53]
	v_mfma_f32_16x16x32_bf16 v[38:41], v[146:149], v[190:193], v[38:41]
	v_mfma_f32_16x16x32_bf16 v[34:37], v[166:169], v[190:193], v[34:37]
	v_mfma_f32_16x16x32_bf16 v[22:25], v[146:149], v[198:201], v[22:25]
	v_mfma_f32_16x16x32_bf16 v[18:21], v[166:169], v[198:201], v[18:21]
	v_mfma_f32_16x16x32_bf16 v[6:9], v[146:149], v[206:209], v[6:9]
	v_mfma_f32_16x16x32_bf16 v[2:5], v[166:169], v[206:209], v[2:5]
	v_mfma_f32_16x16x32_bf16 v[54:57], v[150:153], v[178:181], v[54:57]
	v_mfma_f32_16x16x32_bf16 v[50:53], v[170:173], v[178:181], v[50:53]
	v_mfma_f32_16x16x32_bf16 v[38:41], v[150:153], v[194:197], v[38:41]
	v_mfma_f32_16x16x32_bf16 v[34:37], v[170:173], v[194:197], v[34:37]
	v_mfma_f32_16x16x32_bf16 v[22:25], v[150:153], v[202:205], v[22:25]
	v_mfma_f32_16x16x32_bf16 v[18:21], v[170:173], v[202:205], v[18:21]
	v_mfma_f32_16x16x32_bf16 v[6:9], v[150:153], v[210:213], v[6:9]
	v_mfma_f32_16x16x32_bf16 v[2:5], v[170:173], v[210:213], v[2:5]
	s_setprio 0
	s_barrier
	ds_read_b128 v[130:133], v185 offset:32768
	ds_read_b128 v[134:137], v185 offset:33792
	ds_read_b128 v[138:141], v185 offset:34816
	ds_read_b128 v[142:145], v185 offset:35840
	ds_read_b128 v[146:149], v185 offset:49152
	ds_read_b128 v[150:153], v185 offset:50176
	ds_read_b128 v[166:169], v185 offset:51200
	ds_read_b128 v[170:173], v185 offset:52224
	s_add_u32 s20, s20, s12
	s_addc_u32 s21, s21, s13
	s_mov_b32 m0, s58
	v_lshl_add_u64 v[226:227], s[20:21], 0, v[158:159]
	ds_read_b128 v[174:177], v189 offset:32768
	ds_read_b128 v[178:181], v189 offset:33792
	ds_read_b128 v[190:193], v189 offset:34816
	ds_read_b128 v[194:197], v189 offset:35840
	ds_read_b128 v[198:201], v189 offset:36864
	ds_read_b128 v[202:205], v189 offset:37888
	ds_read_b128 v[206:209], v189 offset:38912
	ds_read_b128 v[210:213], v189 offset:39936
	global_load_lds_dwordx4 v[226:227], off
	s_mov_b32 m0, s59
	v_lshl_add_u64 v[226:227], s[20:21], 0, v[156:157]
	global_load_lds_dwordx4 v[226:227], off
	s_waitcnt vmcnt(8)
	s_waitcnt lgkmcnt(0)
	s_barrier
	s_setprio 1
	v_mfma_f32_16x16x32_bf16 v[126:129], v[130:133], v[174:177], v[126:129]
	v_mfma_f32_16x16x32_bf16 v[122:125], v[138:141], v[174:177], v[122:125]
	v_mfma_f32_16x16x32_bf16 v[110:113], v[130:133], v[190:193], v[110:113]
	v_mfma_f32_16x16x32_bf16 v[106:109], v[138:141], v[190:193], v[106:109]
	v_mfma_f32_16x16x32_bf16 v[94:97], v[130:133], v[198:201], v[94:97]
	v_mfma_f32_16x16x32_bf16 v[90:93], v[138:141], v[198:201], v[90:93]
	v_mfma_f32_16x16x32_bf16 v[78:81], v[130:133], v[206:209], v[78:81]
	v_mfma_f32_16x16x32_bf16 v[74:77], v[138:141], v[206:209], v[74:77]
	v_mfma_f32_16x16x32_bf16 v[126:129], v[134:137], v[178:181], v[126:129]
	v_mfma_f32_16x16x32_bf16 v[122:125], v[142:145], v[178:181], v[122:125]
	v_mfma_f32_16x16x32_bf16 v[110:113], v[134:137], v[194:197], v[110:113]
	v_mfma_f32_16x16x32_bf16 v[106:109], v[142:145], v[194:197], v[106:109]
	v_mfma_f32_16x16x32_bf16 v[94:97], v[134:137], v[202:205], v[94:97]
	v_mfma_f32_16x16x32_bf16 v[90:93], v[142:145], v[202:205], v[90:93]
	v_mfma_f32_16x16x32_bf16 v[78:81], v[134:137], v[210:213], v[78:81]
	v_mfma_f32_16x16x32_bf16 v[74:77], v[142:145], v[210:213], v[74:77]
	v_mfma_f32_16x16x32_bf16 v[118:121], v[146:149], v[174:177], v[118:121]
	v_mfma_f32_16x16x32_bf16 v[114:117], v[166:169], v[174:177], v[114:117]
	v_mfma_f32_16x16x32_bf16 v[102:105], v[146:149], v[190:193], v[102:105]
	v_mfma_f32_16x16x32_bf16 v[98:101], v[166:169], v[190:193], v[98:101]
	v_mfma_f32_16x16x32_bf16 v[86:89], v[146:149], v[198:201], v[86:89]
	v_mfma_f32_16x16x32_bf16 v[82:85], v[166:169], v[198:201], v[82:85]
	v_mfma_f32_16x16x32_bf16 v[70:73], v[146:149], v[206:209], v[70:73]
	v_mfma_f32_16x16x32_bf16 v[66:69], v[166:169], v[206:209], v[66:69]
	v_mfma_f32_16x16x32_bf16 v[118:121], v[150:153], v[178:181], v[118:121]
	v_mfma_f32_16x16x32_bf16 v[114:117], v[170:173], v[178:181], v[114:117]
	v_mfma_f32_16x16x32_bf16 v[102:105], v[150:153], v[194:197], v[102:105]
	v_mfma_f32_16x16x32_bf16 v[98:101], v[170:173], v[194:197], v[98:101]
	v_mfma_f32_16x16x32_bf16 v[86:89], v[150:153], v[202:205], v[86:89]
	v_mfma_f32_16x16x32_bf16 v[82:85], v[170:173], v[202:205], v[82:85]
	v_mfma_f32_16x16x32_bf16 v[70:73], v[150:153], v[210:213], v[70:73]
	v_mfma_f32_16x16x32_bf16 v[66:69], v[170:173], v[210:213], v[66:69]
	s_setprio 0
	s_barrier
; #define PG8_STAGE(bufoff, gbase, voff) do { _Pragma("unroll") for (int _i = 0; _i < 2; ++_i) \
;         __builtin_amdgcn_global_load_lds((const unsigned*)((const char*)(gbase) + (voff)[_i]), (PG8_LAS unsigned*)(lds + (bufoff) + ldsw + _i * 8192), 16, 0, 0); } while (0)
; #define PG8_LDA(dst, b, h) do { _Pragma("unroll") for (int m = 0; m < 4; ++m) _Pragma("unroll") for (int k = 0; k < 2; ++k) dst[m][k] = *(const PG8_LAS bf16x8*)(lds + PG8_SA(b, h) + aoff + m * 2048 + k * 1024); } while (0)
; #define PG8_MMA(ai, bj, At, Bt) do { __builtin_amdgcn_s_setprio(1); _Pragma("unroll") for (int m = 0; m < 4; ++m) _Pragma("unroll") for (int n = 0; n < 2; ++n) _Pragma("unroll") for (int k = 0; k < 2; ++k) \
;         acc[ai][bj][m][n] = __builtin_amdgcn_mfma_f32_16x16x32_bf16(Bt[n][k], At[m][k], acc[ai][bj][m][n], 0, 0, 0); __builtin_amdgcn_s_setprio(0); } while (0)
; #define PG8_WAIT_V(n) asm volatile("s_waitcnt vmcnt(" #n ")" ::: "memory")
; #define PG8_WAIT_L(n) asm volatile("s_waitcnt lgkmcnt(" #n ")" ::: "memory")
; #define PG8_BAR __builtin_amdgcn_s_barrier()
; #define PG8_SCHED __builtin_amdgcn_sched_barrier(0)
; template <class Epi, class Sched, bool ALIGN_EPI = false, bool SP2 = false>
; __device__ __forceinline__ void gemm_phase(PG8_LAS unsigned char* lds, const Gemm g, const Sched& S, const Epi& E) {
;     ...
;         for (int t = 0; t < nt; t += 2) {
;             const bool last = (t == nt - 2);
;             const char* a1 = cA + (size_t)(t + 1) * kstep;
;             const char* a2 = last ? nA : cA + (size_t)(t + 2) * kstep; const char* b2 = last ? nB : cB + (size_t)(t + 2) * kstep;
;             const char* a3 = a2 + kstep; const char* b3 = b2 + kstep;
;     ...
;             PG8_LDA(At, 1, 1); PG8_STAGE(PG8_SB(1, 0), b3, voffB); PG8_STAGE(PG8_SB(1, 1), b3 + hstep, voffB); PG8_STAGE(PG8_SA(1, 0), a3, voffA);
;             PG8_WAIT_V(8); PG8_WAIT_L(0); PG8_BAR; PG8_MMA(1, 0, At, B0); PG8_MMA(1, 1, At, B1); PG8_BAR; PG8_SCHED;
	s_add_i32 m0, s30, 0x17f80
	ds_read_b128 v[174:177], v189 offset:49152
	ds_read_b128 v[178:181], v189 offset:50176
	ds_read_b128 v[190:193], v189 offset:51200
	global_load_lds_dwordx4 v[186:187], off offset:128
	s_add_i32 m0, s30, 0x19f80
	ds_read_b128 v[194:197], v189 offset:52224
	global_load_lds_dwordx4 v[214:215], off offset:128
	s_add_i32 m0, s30, 0x1bf80
	ds_read_b128 v[198:201], v189 offset:53248
	global_load_lds_dwordx4 v[218:219], off offset:128
	s_add_i32 m0, s30, 0x1df80
	ds_read_b128 v[202:205], v189 offset:54272
	global_load_lds_dwordx4 v[220:221], off offset:128
	s_sub_i32 m0, s60, 0x80
	ds_read_b128 v[206:209], v189 offset:55296
	global_load_lds_dwordx4 v[222:223], off offset:128
	s_sub_i32 m0, s61, 0x80
	ds_read_b128 v[210:213], v189 offset:56320
	global_load_lds_dwordx4 v[224:225], off offset:128
	s_waitcnt vmcnt(8)
	s_waitcnt lgkmcnt(0)
	s_barrier
	s_setprio 1
	v_mfma_f32_16x16x32_bf16 v[62:65], v[130:133], v[174:177], v[62:65]
	v_mfma_f32_16x16x32_bf16 v[58:61], v[138:141], v[174:177], v[58:61]
	v_mfma_f32_16x16x32_bf16 v[46:49], v[130:133], v[190:193], v[46:49]
	v_mfma_f32_16x16x32_bf16 v[42:45], v[138:141], v[190:193], v[42:45]
	v_mfma_f32_16x16x32_bf16 v[30:33], v[130:133], v[198:201], v[30:33]
	v_mfma_f32_16x16x32_bf16 v[26:29], v[138:141], v[198:201], v[26:29]
	v_mfma_f32_16x16x32_bf16 v[14:17], v[130:133], v[206:209], v[14:17]
	v_mfma_f32_16x16x32_bf16 v[10:13], v[138:141], v[206:209], v[10:13]
	v_mfma_f32_16x16x32_bf16 v[62:65], v[134:137], v[178:181], v[62:65]
	v_mfma_f32_16x16x32_bf16 v[58:61], v[142:145], v[178:181], v[58:61]
	v_mfma_f32_16x16x32_bf16 v[46:49], v[134:137], v[194:197], v[46:49]
	v_mfma_f32_16x16x32_bf16 v[42:45], v[142:145], v[194:197], v[42:45]
	v_mfma_f32_16x16x32_bf16 v[30:33], v[134:137], v[202:205], v[30:33]
	v_mfma_f32_16x16x32_bf16 v[26:29], v[142:145], v[202:205], v[26:29]
	v_mfma_f32_16x16x32_bf16 v[14:17], v[134:137], v[210:213], v[14:17]
	v_mfma_f32_16x16x32_bf16 v[10:13], v[142:145], v[210:213], v[10:13]
	v_mfma_f32_16x16x32_bf16 v[54:57], v[146:149], v[174:177], v[54:57]
	v_mfma_f32_16x16x32_bf16 v[50:53], v[166:169], v[174:177], v[50:53]
	v_mfma_f32_16x16x32_bf16 v[38:41], v[146:149], v[190:193], v[38:41]
	v_mfma_f32_16x16x32_bf16 v[34:37], v[166:169], v[190:193], v[34:37]
	v_mfma_f32_16x16x32_bf16 v[22:25], v[146:149], v[198:201], v[22:25]
	v_mfma_f32_16x16x32_bf16 v[18:21], v[166:169], v[198:201], v[18:21]
	v_mfma_f32_16x16x32_bf16 v[6:9], v[146:149], v[206:209], v[6:9]
	v_mfma_f32_16x16x32_bf16 v[2:5], v[166:169], v[206:209], v[2:5]
	v_mfma_f32_16x16x32_bf16 v[54:57], v[150:153], v[178:181], v[54:57]
	v_mfma_f32_16x16x32_bf16 v[50:53], v[170:173], v[178:181], v[50:53]
	v_mfma_f32_16x16x32_bf16 v[38:41], v[150:153], v[194:197], v[38:41]
	v_mfma_f32_16x16x32_bf16 v[34:37], v[170:173], v[194:197], v[34:37]
	v_mfma_f32_16x16x32_bf16 v[22:25], v[150:153], v[202:205], v[22:25]
	v_mfma_f32_16x16x32_bf16 v[18:21], v[170:173], v[202:205], v[18:21]
	v_mfma_f32_16x16x32_bf16 v[6:9], v[150:153], v[210:213], v[6:9]
	v_mfma_f32_16x16x32_bf16 v[2:5], v[170:173], v[210:213], v[2:5]
	s_setprio 0
	s_barrier
	s_add_u32 s8, s8, 0x100
	s_addc_u32 s9, s9, 0
	s_add_u32 s52, s52, 0x100
	s_addc_u32 s53, s53, 0
	s_cmp_ge_i32 s69, s62
	s_mov_b32 s20, s69
	s_cbranch_scc0 .LBB0_520

; #define PG8_STAGE(bufoff, gbase, voff) do { _Pragma("unroll") for (int _i = 0; _i < 2; ++_i) \
;         __builtin_amdgcn_global_load_lds((const unsigned*)((const char*)(gbase) + (voff)[_i]), (PG8_LAS unsigned*)(lds + (bufoff) + ldsw + _i * 8192), 16, 0, 0); } while (0)
; #define PG8_LDA(dst, b, h) do { _Pragma("unroll") for (int m = 0; m < 4; ++m) _Pragma("unroll") for (int k = 0; k < 2; ++k) dst[m][k] = *(const PG8_LAS bf16x8*)(lds + PG8_SA(b, h) + aoff + m * 2048 + k * 1024); } while (0)
; #define PG8_LDB(dst, b, h) do { _Pragma("unroll") for (int n = 0; n < 2; ++n) _Pragma("unroll") for (int k = 0; k < 2; ++k) dst[n][k] = *(const PG8_LAS bf16x8*)(lds + PG8_SB(b, h) + boff + n * 2048 + k * 1024); } while (0)
; #define PG8_WAIT_V(n) asm volatile("s_waitcnt vmcnt(" #n ")" ::: "memory")
; #define PG8_WAIT_L(n) asm volatile("s_waitcnt lgkmcnt(" #n ")" ::: "memory")
; #define PG8_BAR __builtin_amdgcn_s_barrier()
; #define PG8_SCHED __builtin_amdgcn_sched_barrier(0)
; template <class Epi, class Sched, bool ALIGN_EPI = false, bool SP2 = false>
; __device__ __forceinline__ void gemm_phase(PG8_LAS unsigned char* lds, const Gemm g, const Sched& S, const Epi& E) {
;     ...
;         const bool has_next = S.next(ui + 1, nxt);
;         const char* nA = has_next ? (const char*)g.A + (size_t)nxt.pm * tstep : cA; const char* nB = has_next ? (const char*)g.Bt + (size_t)nxt.pn * tstep : cB;
;         for (int t = 0; t < nt; t += 2) {
;             const bool last = (t == nt - 2);
;             const char* a1 = cA + (size_t)(t + 1) * kstep;
;             const char* a2 = last ? nA : cA + (size_t)(t + 2) * kstep; const char* b2 = last ? nB : cB + (size_t)(t + 2) * kstep;
;             const char* a3 = a2 + kstep; const char* b3 = b2 + kstep;
;             if (last && has_next) S.a_ready(nxt);
;             if constexpr (SP2) {
;             PG8_LDB(B0, 0, 0); PG8_LDB(B1, 0, 1); PG8_SCHED; PG8_LDA(At, 0, 0); PG8_STAGE(PG8_SA(1, 1), a1 + hstep, voffA);
;             PG8_WAIT_V(8); PG8_WAIT_L(0); PG8_BAR; PG8_MMA(0, 0, At, B0); PG8_MMA(0, 1, At, B1); PG8_BAR; PG8_SCHED;
;             PG8_LDA(At, 0, 1); PG8_STAGE(PG8_SB(0, 0), b2, voffB); PG8_STAGE(PG8_SB(0, 1), b2 + hstep, voffB); PG8_STAGE(PG8_SA(0, 0), a2, voffA);
;             PG8_WAIT_V(8); PG8_WAIT_L(0); PG8_BAR; PG8_MMA(1, 0, At, B0); PG8_MMA(1, 1, At, B1); PG8_BAR; PG8_SCHED;
.LBB0_570:
	s_add_i32 s78, s20, 2
	s_add_u32 s79, s10, 0x80
	s_addc_u32 s21, s11, 0
	s_cmp_eq_u32 s68, s20
	s_cselect_b32 s21, s59, s21
	s_cselect_b32 s20, s58, s79
	s_cselect_b32 s81, s61, s63
	s_cselect_b32 s80, s60, s62
	ds_read_b128 v[82:85], v246
	ds_read_b128 v[98:101], v246 offset:1024
	ds_read_b128 v[102:105], v246 offset:2048
	ds_read_b128 v[106:109], v246 offset:3072
	ds_read_b128 v[146:149], v246 offset:16384
	ds_read_b128 v[150:153], v246 offset:17408
	ds_read_b128 v[154:157], v246 offset:18432
	ds_read_b128 v[158:161], v246 offset:19456
	v_lshl_add_u64 v[194:195], s[10:11], 0, v[224:225]
	s_add_i32 m0, s64, 0xc000
	ds_read_b128 v[162:165], v249
	ds_read_b128 v[166:169], v249 offset:1024
	ds_read_b128 v[170:173], v249 offset:2048
	ds_read_b128 v[174:177], v249 offset:3072
	ds_read_b128 v[178:181], v249 offset:4096
	ds_read_b128 v[182:185], v249 offset:5120
	ds_read_b128 v[186:189], v249 offset:6144
	ds_read_b128 v[190:193], v249 offset:7168
	global_load_lds_dwordx4 v[194:195], off
	s_add_i32 m0, s64, 0xe000
	v_lshl_add_u64 v[194:195], s[10:11], 0, v[226:227]
	global_load_lds_dwordx4 v[194:195], off
	s_waitcnt vmcnt(8)
	s_waitcnt lgkmcnt(0)
	s_barrier
	s_setprio 1
	v_mfma_f32_16x16x32_bf16 v[142:145], v[82:85], v[162:165], v[142:145]
	v_mfma_f32_16x16x32_bf16 v[138:141], v[102:105], v[162:165], v[138:141]
	v_mfma_f32_16x16x32_bf16 v[126:129], v[82:85], v[170:173], v[126:129]
	v_mfma_f32_16x16x32_bf16 v[122:125], v[102:105], v[170:173], v[122:125]
	v_mfma_f32_16x16x32_bf16 v[110:113], v[82:85], v[178:181], v[110:113]
	v_mfma_f32_16x16x32_bf16 v[94:97], v[102:105], v[178:181], v[94:97]
	v_mfma_f32_16x16x32_bf16 v[78:81], v[82:85], v[186:189], v[78:81]
	v_mfma_f32_16x16x32_bf16 v[74:77], v[102:105], v[186:189], v[74:77]
	v_mfma_f32_16x16x32_bf16 v[142:145], v[98:101], v[166:169], v[142:145]
	v_mfma_f32_16x16x32_bf16 v[138:141], v[106:109], v[166:169], v[138:141]
	v_mfma_f32_16x16x32_bf16 v[126:129], v[98:101], v[174:177], v[126:129]
	v_mfma_f32_16x16x32_bf16 v[122:125], v[106:109], v[174:177], v[122:125]
	v_mfma_f32_16x16x32_bf16 v[110:113], v[98:101], v[182:185], v[110:113]
	v_mfma_f32_16x16x32_bf16 v[94:97], v[106:109], v[182:185], v[94:97]
	v_mfma_f32_16x16x32_bf16 v[78:81], v[98:101], v[190:193], v[78:81]
	v_mfma_f32_16x16x32_bf16 v[74:77], v[106:109], v[190:193], v[74:77]
	v_mfma_f32_16x16x32_bf16 v[134:137], v[146:149], v[162:165], v[134:137]
	v_mfma_f32_16x16x32_bf16 v[130:133], v[154:157], v[162:165], v[130:133]
	v_mfma_f32_16x16x32_bf16 v[118:121], v[146:149], v[170:173], v[118:121]
	v_mfma_f32_16x16x32_bf16 v[114:117], v[154:157], v[170:173], v[114:117]
	v_mfma_f32_16x16x32_bf16 v[90:93], v[146:149], v[178:181], v[90:93]
	v_mfma_f32_16x16x32_bf16 v[86:89], v[154:157], v[178:181], v[86:89]
	v_mfma_f32_16x16x32_bf16 v[70:73], v[146:149], v[186:189], v[70:73]
	v_mfma_f32_16x16x32_bf16 v[66:69], v[154:157], v[186:189], v[66:69]
	v_mfma_f32_16x16x32_bf16 v[134:137], v[150:153], v[166:169], v[134:137]
	v_mfma_f32_16x16x32_bf16 v[130:133], v[158:161], v[166:169], v[130:133]
	v_mfma_f32_16x16x32_bf16 v[118:121], v[150:153], v[174:177], v[118:121]
	v_mfma_f32_16x16x32_bf16 v[114:117], v[158:161], v[174:177], v[114:117]
	v_mfma_f32_16x16x32_bf16 v[90:93], v[150:153], v[182:185], v[90:93]
	v_mfma_f32_16x16x32_bf16 v[86:89], v[158:161], v[182:185], v[86:89]
	v_mfma_f32_16x16x32_bf16 v[70:73], v[150:153], v[190:193], v[70:73]
	v_mfma_f32_16x16x32_bf16 v[66:69], v[158:161], v[190:193], v[66:69]
	s_setprio 0
	s_barrier
	v_lshl_add_u64 v[194:195], s[80:81], 0, v[0:1]
	s_add_i32 m0, s22, 0x10000
	ds_read_b128 v[162:165], v249 offset:16384
	ds_read_b128 v[166:169], v249 offset:17408
	ds_read_b128 v[170:173], v249 offset:18432
	ds_read_b128 v[174:177], v249 offset:19456
	ds_read_b128 v[178:181], v249 offset:20480
	ds_read_b128 v[182:185], v249 offset:21504
	ds_read_b128 v[186:189], v249 offset:22528
	ds_read_b128 v[190:193], v249 offset:23552
	global_load_lds_dwordx4 v[194:195], off
	s_add_i32 m0, s22, 0x12000
	v_lshl_add_u64 v[196:197], s[80:81], 0, v[218:219]
	s_add_u32 s80, s80, s46
	s_addc_u32 s81, s81, s47
	global_load_lds_dwordx4 v[196:197], off
	v_lshl_add_u64 v[198:199], s[80:81], 0, v[0:1]
	s_add_i32 m0, s22, 0x14000
	v_lshl_add_u64 v[200:201], s[80:81], 0, v[218:219]
	global_load_lds_dwordx4 v[198:199], off
	s_add_i32 m0, s22, 0x16000
	v_lshl_add_u64 v[202:203], s[20:21], 0, v[0:1]
	global_load_lds_dwordx4 v[200:201], off
	s_mov_b32 m0, s64
	v_lshl_add_u64 v[204:205], s[20:21], 0, v[218:219]
	global_load_lds_dwordx4 v[202:203], off
	s_mov_b32 m0, s30
	s_nop 0
	global_load_lds_dwordx4 v[204:205], off
	s_waitcnt vmcnt(8)
	s_waitcnt lgkmcnt(0)
	s_barrier
; #define PG8_STAGE(bufoff, gbase, voff) do { _Pragma("unroll") for (int _i = 0; _i < 2; ++_i) \
;         __builtin_amdgcn_global_load_lds((const unsigned*)((const char*)(gbase) + (voff)[_i]), (PG8_LAS unsigned*)(lds + (bufoff) + ldsw + _i * 8192), 16, 0, 0); } while (0)
; #define PG8_LDA(dst, b, h) do { _Pragma("unroll") for (int m = 0; m < 4; ++m) _Pragma("unroll") for (int k = 0; k < 2; ++k) dst[m][k] = *(const PG8_LAS bf16x8*)(lds + PG8_SA(b, h) + aoff + m * 2048 + k * 1024); } while (0)
; #define PG8_LDB(dst, b, h) do { _Pragma("unroll") for (int n = 0; n < 2; ++n) _Pragma("unroll") for (int k = 0; k < 2; ++k) dst[n][k] = *(const PG8_LAS bf16x8*)(lds + PG8_SB(b, h) + boff + n * 2048 + k * 1024); } while (0)
; #define PG8_MMA(ai, bj, At, Bt) do { __builtin_amdgcn_s_setprio(1); _Pragma("unroll") for (int m = 0; m < 4; ++m) _Pragma("unroll") for (int n = 0; n < 2; ++n) _Pragma("unroll") for (int k = 0; k < 2; ++k) \
;         acc[ai][bj][m][n] = __builtin_amdgcn_mfma_f32_16x16x32_bf16(Bt[n][k], At[m][k], acc[ai][bj][m][n], 0, 0, 0); __builtin_amdgcn_s_setprio(0); } while (0)
; #define PG8_WAIT_V(n) asm volatile("s_waitcnt vmcnt(" #n ")" ::: "memory")
; #define PG8_WAIT_L(n) asm volatile("s_waitcnt lgkmcnt(" #n ")" ::: "memory")
; #define PG8_BAR __builtin_amdgcn_s_barrier()
; #define PG8_SCHED __builtin_amdgcn_sched_barrier(0)
; template <class Epi, class Sched, bool ALIGN_EPI = false, bool SP2 = false>
; __device__ __forceinline__ void gemm_phase(PG8_LAS unsigned char* lds, const Gemm g, const Sched& S, const Epi& E) {
;     ...
;             PG8_WAIT_V(8); PG8_WAIT_L(0); PG8_BAR; PG8_MMA(1, 0, At, B0); PG8_MMA(1, 1, At, B1); PG8_BAR; PG8_SCHED;
;             PG8_LDB(B0, 1, 0); PG8_LDB(B1, 1, 1); PG8_SCHED; PG8_LDA(At, 1, 0); PG8_STAGE(PG8_SA(0, 1), a2 + hstep, voffA);
;             PG8_WAIT_V(8); PG8_WAIT_L(0); PG8_BAR; PG8_MMA(0, 0, At, B0); PG8_MMA(0, 1, At, B1); PG8_BAR; PG8_SCHED;
	s_setprio 1
	v_mfma_f32_16x16x32_bf16 v[62:65], v[82:85], v[162:165], v[62:65]
	v_mfma_f32_16x16x32_bf16 v[58:61], v[102:105], v[162:165], v[58:61]
	v_mfma_f32_16x16x32_bf16 v[46:49], v[82:85], v[170:173], v[46:49]
	v_mfma_f32_16x16x32_bf16 v[42:45], v[102:105], v[170:173], v[42:45]
	v_mfma_f32_16x16x32_bf16 v[30:33], v[82:85], v[178:181], v[30:33]
	v_mfma_f32_16x16x32_bf16 v[26:29], v[102:105], v[178:181], v[26:29]
	v_mfma_f32_16x16x32_bf16 v[14:17], v[82:85], v[186:189], v[14:17]
	v_mfma_f32_16x16x32_bf16 v[10:13], v[102:105], v[186:189], v[10:13]
	v_mfma_f32_16x16x32_bf16 v[62:65], v[98:101], v[166:169], v[62:65]
	v_mfma_f32_16x16x32_bf16 v[58:61], v[106:109], v[166:169], v[58:61]
	v_mfma_f32_16x16x32_bf16 v[46:49], v[98:101], v[174:177], v[46:49]
	v_mfma_f32_16x16x32_bf16 v[42:45], v[106:109], v[174:177], v[42:45]
	v_mfma_f32_16x16x32_bf16 v[30:33], v[98:101], v[182:185], v[30:33]
	v_mfma_f32_16x16x32_bf16 v[26:29], v[106:109], v[182:185], v[26:29]
	v_mfma_f32_16x16x32_bf16 v[14:17], v[98:101], v[190:193], v[14:17]
	v_mfma_f32_16x16x32_bf16 v[10:13], v[106:109], v[190:193], v[10:13]
	v_mfma_f32_16x16x32_bf16 v[54:57], v[146:149], v[162:165], v[54:57]
	v_mfma_f32_16x16x32_bf16 v[50:53], v[154:157], v[162:165], v[50:53]
	v_mfma_f32_16x16x32_bf16 v[38:41], v[146:149], v[170:173], v[38:41]
	v_mfma_f32_16x16x32_bf16 v[34:37], v[154:157], v[170:173], v[34:37]
	v_mfma_f32_16x16x32_bf16 v[22:25], v[146:149], v[178:181], v[22:25]
	v_mfma_f32_16x16x32_bf16 v[18:21], v[154:157], v[178:181], v[18:21]
	v_mfma_f32_16x16x32_bf16 v[6:9], v[146:149], v[186:189], v[6:9]
	v_mfma_f32_16x16x32_bf16 v[2:5], v[154:157], v[186:189], v[2:5]
	v_mfma_f32_16x16x32_bf16 v[54:57], v[150:153], v[166:169], v[54:57]
	v_mfma_f32_16x16x32_bf16 v[50:53], v[158:161], v[166:169], v[50:53]
	v_mfma_f32_16x16x32_bf16 v[38:41], v[150:153], v[174:177], v[38:41]
	v_mfma_f32_16x16x32_bf16 v[34:37], v[158:161], v[174:177], v[34:37]
	v_mfma_f32_16x16x32_bf16 v[22:25], v[150:153], v[182:185], v[22:25]
	v_mfma_f32_16x16x32_bf16 v[18:21], v[158:161], v[182:185], v[18:21]
	v_mfma_f32_16x16x32_bf16 v[6:9], v[150:153], v[190:193], v[6:9]
	v_mfma_f32_16x16x32_bf16 v[2:5], v[158:161], v[190:193], v[2:5]
	s_setprio 0
	s_barrier
	ds_read_b128 v[82:85], v246 offset:32768
	ds_read_b128 v[98:101], v246 offset:33792
	ds_read_b128 v[102:105], v246 offset:34816
	ds_read_b128 v[106:109], v246 offset:35840
	ds_read_b128 v[146:149], v246 offset:49152
	ds_read_b128 v[150:153], v246 offset:50176
	ds_read_b128 v[154:157], v246 offset:51200
	ds_read_b128 v[158:161], v246 offset:52224
	s_add_u32 s20, s20, s46
	s_addc_u32 s21, s21, s47
	s_mov_b32 m0, s31
	v_lshl_add_u64 v[206:207], s[20:21], 0, v[0:1]
	ds_read_b128 v[162:165], v249 offset:32768
	ds_read_b128 v[166:169], v249 offset:33792
	ds_read_b128 v[170:173], v249 offset:34816
	ds_read_b128 v[174:177], v249 offset:35840
	ds_read_b128 v[178:181], v249 offset:36864
	ds_read_b128 v[182:185], v249 offset:37888
	ds_read_b128 v[186:189], v249 offset:38912
	ds_read_b128 v[190:193], v249 offset:39936
	global_load_lds_dwordx4 v[206:207], off
	s_mov_b32 m0, s33
	v_lshl_add_u64 v[206:207], s[20:21], 0, v[218:219]
	global_load_lds_dwordx4 v[206:207], off
	s_waitcnt vmcnt(8)
	s_waitcnt lgkmcnt(0)
	s_barrier
	s_setprio 1
	v_mfma_f32_16x16x32_bf16 v[142:145], v[82:85], v[162:165], v[142:145]
	v_mfma_f32_16x16x32_bf16 v[138:141], v[102:105], v[162:165], v[138:141]
	v_mfma_f32_16x16x32_bf16 v[126:129], v[82:85], v[170:173], v[126:129]
	v_mfma_f32_16x16x32_bf16 v[122:125], v[102:105], v[170:173], v[122:125]
	v_mfma_f32_16x16x32_bf16 v[110:113], v[82:85], v[178:181], v[110:113]
	v_mfma_f32_16x16x32_bf16 v[94:97], v[102:105], v[178:181], v[94:97]
	v_mfma_f32_16x16x32_bf16 v[78:81], v[82:85], v[186:189], v[78:81]
	v_mfma_f32_16x16x32_bf16 v[74:77], v[102:105], v[186:189], v[74:77]
	v_mfma_f32_16x16x32_bf16 v[142:145], v[98:101], v[166:169], v[142:145]
	v_mfma_f32_16x16x32_bf16 v[138:141], v[106:109], v[166:169], v[138:141]
	v_mfma_f32_16x16x32_bf16 v[126:129], v[98:101], v[174:177], v[126:129]
	v_mfma_f32_16x16x32_bf16 v[122:125], v[106:109], v[174:177], v[122:125]
	v_mfma_f32_16x16x32_bf16 v[110:113], v[98:101], v[182:185], v[110:113]
	v_mfma_f32_16x16x32_bf16 v[94:97], v[106:109], v[182:185], v[94:97]
	v_mfma_f32_16x16x32_bf16 v[78:81], v[98:101], v[190:193], v[78:81]
	v_mfma_f32_16x16x32_bf16 v[74:77], v[106:109], v[190:193], v[74:77]
	v_mfma_f32_16x16x32_bf16 v[134:137], v[146:149], v[162:165], v[134:137]
	v_mfma_f32_16x16x32_bf16 v[130:133], v[154:157], v[162:165], v[130:133]
	v_mfma_f32_16x16x32_bf16 v[118:121], v[146:149], v[170:173], v[118:121]
	v_mfma_f32_16x16x32_bf16 v[114:117], v[154:157], v[170:173], v[114:117]
	v_mfma_f32_16x16x32_bf16 v[90:93], v[146:149], v[178:181], v[90:93]
	v_mfma_f32_16x16x32_bf16 v[86:89], v[154:157], v[178:181], v[86:89]
	v_mfma_f32_16x16x32_bf16 v[70:73], v[146:149], v[186:189], v[70:73]
	v_mfma_f32_16x16x32_bf16 v[66:69], v[154:157], v[186:189], v[66:69]
	v_mfma_f32_16x16x32_bf16 v[134:137], v[150:153], v[166:169], v[134:137]
	v_mfma_f32_16x16x32_bf16 v[130:133], v[158:161], v[166:169], v[130:133]
	v_mfma_f32_16x16x32_bf16 v[118:121], v[150:153], v[174:177], v[118:121]
	v_mfma_f32_16x16x32_bf16 v[114:117], v[158:161], v[174:177], v[114:117]
	v_mfma_f32_16x16x32_bf16 v[90:93], v[150:153], v[182:185], v[90:93]
	v_mfma_f32_16x16x32_bf16 v[86:89], v[158:161], v[182:185], v[86:89]
	v_mfma_f32_16x16x32_bf16 v[70:73], v[150:153], v[190:193], v[70:73]
	v_mfma_f32_16x16x32_bf16 v[66:69], v[158:161], v[190:193], v[66:69]
	s_setprio 0
	s_barrier
; #define PG8_STAGE(bufoff, gbase, voff) do { _Pragma("unroll") for (int _i = 0; _i < 2; ++_i) \
;         __builtin_amdgcn_global_load_lds((const unsigned*)((const char*)(gbase) + (voff)[_i]), (PG8_LAS unsigned*)(lds + (bufoff) + ldsw + _i * 8192), 16, 0, 0); } while (0)
; #define PG8_LDA(dst, b, h) do { _Pragma("unroll") for (int m = 0; m < 4; ++m) _Pragma("unroll") for (int k = 0; k < 2; ++k) dst[m][k] = *(const PG8_LAS bf16x8*)(lds + PG8_SA(b, h) + aoff + m * 2048 + k * 1024); } while (0)
; #define PG8_MMA(ai, bj, At, Bt) do { __builtin_amdgcn_s_setprio(1); _Pragma("unroll") for (int m = 0; m < 4; ++m) _Pragma("unroll") for (int n = 0; n < 2; ++n) _Pragma("unroll") for (int k = 0; k < 2; ++k) \
;         acc[ai][bj][m][n] = __builtin_amdgcn_mfma_f32_16x16x32_bf16(Bt[n][k], At[m][k], acc[ai][bj][m][n], 0, 0, 0); __builtin_amdgcn_s_setprio(0); } while (0)
; #define PG8_WAIT_V(n) asm volatile("s_waitcnt vmcnt(" #n ")" ::: "memory")
; #define PG8_WAIT_L(n) asm volatile("s_waitcnt lgkmcnt(" #n ")" ::: "memory")
; #define PG8_BAR __builtin_amdgcn_s_barrier()
; #define PG8_SCHED __builtin_amdgcn_sched_barrier(0)
; template <class Epi, class Sched, bool ALIGN_EPI = false, bool SP2 = false>
; __device__ __forceinline__ void gemm_phase(PG8_LAS unsigned char* lds, const Gemm g, const Sched& S, const Epi& E) {
;     ...
;         for (int t = 0; t < nt; t += 2) {
;             const bool last = (t == nt - 2);
;             const char* a1 = cA + (size_t)(t + 1) * kstep;
;             const char* a2 = last ? nA : cA + (size_t)(t + 2) * kstep; const char* b2 = last ? nB : cB + (size_t)(t + 2) * kstep;
;             const char* a3 = a2 + kstep; const char* b3 = b2 + kstep;
;     ...
;             PG8_LDA(At, 1, 1); PG8_STAGE(PG8_SB(1, 0), b3, voffB); PG8_STAGE(PG8_SB(1, 1), b3 + hstep, voffB); PG8_STAGE(PG8_SA(1, 0), a3, voffA);
;             PG8_WAIT_V(8); PG8_WAIT_L(0); PG8_BAR; PG8_MMA(1, 0, At, B0); PG8_MMA(1, 1, At, B1); PG8_BAR; PG8_SCHED;
	s_add_i32 m0, s22, 0x17f80
	ds_read_b128 v[162:165], v249 offset:49152
	ds_read_b128 v[166:169], v249 offset:50176
	ds_read_b128 v[170:173], v249 offset:51200
	global_load_lds_dwordx4 v[194:195], off offset:128
	s_add_i32 m0, s22, 0x19f80
	ds_read_b128 v[174:177], v249 offset:52224
	global_load_lds_dwordx4 v[196:197], off offset:128
	s_add_i32 m0, s22, 0x1bf80
	ds_read_b128 v[178:181], v249 offset:53248
	global_load_lds_dwordx4 v[198:199], off offset:128
	s_add_i32 m0, s22, 0x1df80
	ds_read_b128 v[182:185], v249 offset:54272
	global_load_lds_dwordx4 v[200:201], off offset:128
	s_sub_i32 m0, s39, 0x80
	ds_read_b128 v[186:189], v249 offset:55296
	global_load_lds_dwordx4 v[202:203], off offset:128
	s_sub_i32 m0, s65, 0x80
	ds_read_b128 v[190:193], v249 offset:56320
	global_load_lds_dwordx4 v[204:205], off offset:128
	s_waitcnt vmcnt(8)
	s_waitcnt lgkmcnt(0)
	s_barrier
	s_setprio 1
	v_mfma_f32_16x16x32_bf16 v[62:65], v[82:85], v[162:165], v[62:65]
	v_mfma_f32_16x16x32_bf16 v[58:61], v[102:105], v[162:165], v[58:61]
	v_mfma_f32_16x16x32_bf16 v[46:49], v[82:85], v[170:173], v[46:49]
	v_mfma_f32_16x16x32_bf16 v[42:45], v[102:105], v[170:173], v[42:45]
	v_mfma_f32_16x16x32_bf16 v[30:33], v[82:85], v[178:181], v[30:33]
	v_mfma_f32_16x16x32_bf16 v[26:29], v[102:105], v[178:181], v[26:29]
	v_mfma_f32_16x16x32_bf16 v[14:17], v[82:85], v[186:189], v[14:17]
	v_mfma_f32_16x16x32_bf16 v[10:13], v[102:105], v[186:189], v[10:13]
	v_mfma_f32_16x16x32_bf16 v[62:65], v[98:101], v[166:169], v[62:65]
	v_mfma_f32_16x16x32_bf16 v[58:61], v[106:109], v[166:169], v[58:61]
	v_mfma_f32_16x16x32_bf16 v[46:49], v[98:101], v[174:177], v[46:49]
	v_mfma_f32_16x16x32_bf16 v[42:45], v[106:109], v[174:177], v[42:45]
	v_mfma_f32_16x16x32_bf16 v[30:33], v[98:101], v[182:185], v[30:33]
	v_mfma_f32_16x16x32_bf16 v[26:29], v[106:109], v[182:185], v[26:29]
	v_mfma_f32_16x16x32_bf16 v[14:17], v[98:101], v[190:193], v[14:17]
	v_mfma_f32_16x16x32_bf16 v[10:13], v[106:109], v[190:193], v[10:13]
	v_mfma_f32_16x16x32_bf16 v[54:57], v[146:149], v[162:165], v[54:57]
	v_mfma_f32_16x16x32_bf16 v[50:53], v[154:157], v[162:165], v[50:53]
	v_mfma_f32_16x16x32_bf16 v[38:41], v[146:149], v[170:173], v[38:41]
	v_mfma_f32_16x16x32_bf16 v[34:37], v[154:157], v[170:173], v[34:37]
	v_mfma_f32_16x16x32_bf16 v[22:25], v[146:149], v[178:181], v[22:25]
	v_mfma_f32_16x16x32_bf16 v[18:21], v[154:157], v[178:181], v[18:21]
	v_mfma_f32_16x16x32_bf16 v[6:9], v[146:149], v[186:189], v[6:9]
	v_mfma_f32_16x16x32_bf16 v[2:5], v[154:157], v[186:189], v[2:5]
	v_mfma_f32_16x16x32_bf16 v[54:57], v[150:153], v[166:169], v[54:57]
	v_mfma_f32_16x16x32_bf16 v[50:53], v[158:161], v[166:169], v[50:53]
	v_mfma_f32_16x16x32_bf16 v[38:41], v[150:153], v[174:177], v[38:41]
	v_mfma_f32_16x16x32_bf16 v[34:37], v[158:161], v[174:177], v[34:37]
	v_mfma_f32_16x16x32_bf16 v[22:25], v[150:153], v[182:185], v[22:25]
	v_mfma_f32_16x16x32_bf16 v[18:21], v[158:161], v[182:185], v[18:21]
	v_mfma_f32_16x16x32_bf16 v[6:9], v[150:153], v[190:193], v[6:9]
	v_mfma_f32_16x16x32_bf16 v[2:5], v[158:161], v[190:193], v[2:5]
	s_setprio 0
	s_barrier
	s_add_u32 s10, s10, 0x100
	s_addc_u32 s11, s11, 0
	s_add_u32 s62, s62, 0x100
	s_addc_u32 s63, s63, 0
	s_cmp_ge_i32 s78, s67
	s_mov_b32 s20, s78
	s_cbranch_scc0 .LBB0_570

; #define PG8_STAGE(bufoff, gbase, voff) do { _Pragma("unroll") for (int _i = 0; _i < 2; ++_i) \
;         __builtin_amdgcn_global_load_lds((const unsigned*)((const char*)(gbase) + (voff)[_i]), (PG8_LAS unsigned*)(lds + (bufoff) + ldsw + _i * 8192), 16, 0, 0); } while (0)
; #define PG8_LDA(dst, b, h) do { _Pragma("unroll") for (int m = 0; m < 4; ++m) _Pragma("unroll") for (int k = 0; k < 2; ++k) dst[m][k] = *(const PG8_LAS bf16x8*)(lds + PG8_SA(b, h) + aoff + m * 2048 + k * 1024); } while (0)
; #define PG8_LDB(dst, b, h) do { _Pragma("unroll") for (int n = 0; n < 2; ++n) _Pragma("unroll") for (int k = 0; k < 2; ++k) dst[n][k] = *(const PG8_LAS bf16x8*)(lds + PG8_SB(b, h) + boff + n * 2048 + k * 1024); } while (0)
; #define PG8_WAIT_V(n) asm volatile("s_waitcnt vmcnt(" #n ")" ::: "memory")
; #define PG8_WAIT_L(n) asm volatile("s_waitcnt lgkmcnt(" #n ")" ::: "memory")
; #define PG8_BAR __builtin_amdgcn_s_barrier()
; #define PG8_SCHED __builtin_amdgcn_sched_barrier(0)
; template <class Epi, class Sched, bool ALIGN_EPI = false, bool SP2 = false>
; __device__ __forceinline__ void gemm_phase(PG8_LAS unsigned char* lds, const Gemm g, const Sched& S, const Epi& E) {
;     ...
;         const bool has_next = S.next(ui + 1, nxt);
;         const char* nA = has_next ? (const char*)g.A + (size_t)nxt.pm * tstep : cA; const char* nB = has_next ? (const char*)g.Bt + (size_t)nxt.pn * tstep : cB;
;         for (int t = 0; t < nt; t += 2) {
;             const bool last = (t == nt - 2);
;             const char* a1 = cA + (size_t)(t + 1) * kstep;
;             const char* a2 = last ? nA : cA + (size_t)(t + 2) * kstep; const char* b2 = last ? nB : cB + (size_t)(t + 2) * kstep;
;             const char* a3 = a2 + kstep; const char* b3 = b2 + kstep;
;             if (last && has_next) S.a_ready(nxt);
;             if constexpr (SP2) {
;             PG8_LDB(B0, 0, 0); PG8_LDB(B1, 0, 1); PG8_SCHED; PG8_LDA(At, 0, 0); PG8_STAGE(PG8_SA(1, 1), a1 + hstep, voffA);
;             PG8_WAIT_V(8); PG8_WAIT_L(0); PG8_BAR; PG8_MMA(0, 0, At, B0); PG8_MMA(0, 1, At, B1); PG8_BAR; PG8_SCHED;
;             PG8_LDA(At, 0, 1); PG8_STAGE(PG8_SB(0, 0), b2, voffB); PG8_STAGE(PG8_SB(0, 1), b2 + hstep, voffB); PG8_STAGE(PG8_SA(0, 0), a2, voffA);
;             PG8_WAIT_V(8); PG8_WAIT_L(0); PG8_BAR; PG8_MMA(1, 0, At, B0); PG8_MMA(1, 1, At, B1); PG8_BAR; PG8_SCHED;
.LBB0_641:
	s_add_i32 s68, s20, 2
	s_add_u32 s69, s8, 0x80
	s_addc_u32 s21, s9, 0
	s_cmp_eq_u32 s63, s20
	s_cselect_b32 s21, s49, s21
	s_cselect_b32 s20, s48, s69
	s_cselect_b32 s71, s51, s53
	s_cselect_b32 s70, s50, s52
	ds_read_b128 v[130:133], v181
	ds_read_b128 v[134:137], v181 offset:1024
	ds_read_b128 v[138:141], v181 offset:2048
	ds_read_b128 v[142:145], v181 offset:3072
	ds_read_b128 v[146:149], v181 offset:16384
	ds_read_b128 v[150:153], v181 offset:17408
	ds_read_b128 v[166:169], v181 offset:18432
	ds_read_b128 v[170:173], v181 offset:19456
	v_lshl_add_u64 v[178:179], s[8:9], 0, v[162:163]
	s_add_i32 m0, s55, 0xc000
	ds_read_b128 v[174:177], v183
	ds_read_b128 v[184:187], v183 offset:1024
	ds_read_b128 v[188:191], v183 offset:2048
	ds_read_b128 v[192:195], v183 offset:3072
	ds_read_b128 v[196:199], v183 offset:4096
	ds_read_b128 v[200:203], v183 offset:5120
	ds_read_b128 v[204:207], v183 offset:6144
	ds_read_b128 v[208:211], v183 offset:7168
	global_load_lds_dwordx4 v[178:179], off
	s_add_i32 m0, s55, 0xe000
	v_lshl_add_u64 v[178:179], s[8:9], 0, v[164:165]
	global_load_lds_dwordx4 v[178:179], off
	s_waitcnt vmcnt(8)
	s_waitcnt lgkmcnt(0)
	s_barrier
	s_setprio 1
	v_mfma_f32_16x16x32_bf16 v[122:125], v[130:133], v[174:177], v[122:125]
	v_mfma_f32_16x16x32_bf16 v[118:121], v[138:141], v[174:177], v[118:121]
	v_mfma_f32_16x16x32_bf16 v[106:109], v[130:133], v[188:191], v[106:109]
	v_mfma_f32_16x16x32_bf16 v[102:105], v[138:141], v[188:191], v[102:105]
	v_mfma_f32_16x16x32_bf16 v[90:93], v[130:133], v[196:199], v[90:93]
	v_mfma_f32_16x16x32_bf16 v[86:89], v[138:141], v[196:199], v[86:89]
	v_mfma_f32_16x16x32_bf16 v[74:77], v[130:133], v[204:207], v[74:77]
	v_mfma_f32_16x16x32_bf16 v[70:73], v[138:141], v[204:207], v[70:73]
	v_mfma_f32_16x16x32_bf16 v[122:125], v[134:137], v[184:187], v[122:125]
	v_mfma_f32_16x16x32_bf16 v[118:121], v[142:145], v[184:187], v[118:121]
	v_mfma_f32_16x16x32_bf16 v[106:109], v[134:137], v[192:195], v[106:109]
	v_mfma_f32_16x16x32_bf16 v[102:105], v[142:145], v[192:195], v[102:105]
	v_mfma_f32_16x16x32_bf16 v[90:93], v[134:137], v[200:203], v[90:93]
	v_mfma_f32_16x16x32_bf16 v[86:89], v[142:145], v[200:203], v[86:89]
	v_mfma_f32_16x16x32_bf16 v[74:77], v[134:137], v[208:211], v[74:77]
	v_mfma_f32_16x16x32_bf16 v[70:73], v[142:145], v[208:211], v[70:73]
	v_mfma_f32_16x16x32_bf16 v[126:129], v[146:149], v[174:177], v[126:129]
	v_mfma_f32_16x16x32_bf16 v[114:117], v[166:169], v[174:177], v[114:117]
	v_mfma_f32_16x16x32_bf16 v[110:113], v[146:149], v[188:191], v[110:113]
	v_mfma_f32_16x16x32_bf16 v[98:101], v[166:169], v[188:191], v[98:101]
	v_mfma_f32_16x16x32_bf16 v[94:97], v[146:149], v[196:199], v[94:97]
	v_mfma_f32_16x16x32_bf16 v[82:85], v[166:169], v[196:199], v[82:85]
	v_mfma_f32_16x16x32_bf16 v[78:81], v[146:149], v[204:207], v[78:81]
	v_mfma_f32_16x16x32_bf16 v[66:69], v[166:169], v[204:207], v[66:69]
	v_mfma_f32_16x16x32_bf16 v[126:129], v[150:153], v[184:187], v[126:129]
	v_mfma_f32_16x16x32_bf16 v[114:117], v[170:173], v[184:187], v[114:117]
	v_mfma_f32_16x16x32_bf16 v[110:113], v[150:153], v[192:195], v[110:113]
	v_mfma_f32_16x16x32_bf16 v[98:101], v[170:173], v[192:195], v[98:101]
	v_mfma_f32_16x16x32_bf16 v[94:97], v[150:153], v[200:203], v[94:97]
	v_mfma_f32_16x16x32_bf16 v[82:85], v[170:173], v[200:203], v[82:85]
	v_mfma_f32_16x16x32_bf16 v[78:81], v[150:153], v[208:211], v[78:81]
	v_mfma_f32_16x16x32_bf16 v[66:69], v[170:173], v[208:211], v[66:69]
	s_setprio 0
	s_barrier
	v_lshl_add_u64 v[178:179], s[70:71], 0, v[0:1]
	s_add_i32 m0, s23, 0x10000
	ds_read_b128 v[174:177], v183 offset:16384
	ds_read_b128 v[184:187], v183 offset:17408
	ds_read_b128 v[188:191], v183 offset:18432
	ds_read_b128 v[192:195], v183 offset:19456
	ds_read_b128 v[196:199], v183 offset:20480
	ds_read_b128 v[200:203], v183 offset:21504
	ds_read_b128 v[204:207], v183 offset:22528
	ds_read_b128 v[208:211], v183 offset:23552
	global_load_lds_dwordx4 v[178:179], off
	s_add_i32 m0, s23, 0x12000
	v_lshl_add_u64 v[212:213], s[70:71], 0, v[154:155]
	s_add_u32 s70, s70, s10
	s_addc_u32 s71, s71, s11
	global_load_lds_dwordx4 v[212:213], off
	v_lshl_add_u64 v[214:215], s[70:71], 0, v[0:1]
	s_add_i32 m0, s23, 0x14000
	v_lshl_add_u64 v[218:219], s[70:71], 0, v[154:155]
	global_load_lds_dwordx4 v[214:215], off
	s_add_i32 m0, s23, 0x16000
	v_lshl_add_u64 v[220:221], s[20:21], 0, v[158:159]
	global_load_lds_dwordx4 v[218:219], off
	s_mov_b32 m0, s55
	v_lshl_add_u64 v[222:223], s[20:21], 0, v[156:157]
	global_load_lds_dwordx4 v[220:221], off
	s_mov_b32 m0, s56
	s_nop 0
	global_load_lds_dwordx4 v[222:223], off
	s_waitcnt vmcnt(8)
	s_waitcnt lgkmcnt(0)
	s_barrier
; #define PG8_STAGE(bufoff, gbase, voff) do { _Pragma("unroll") for (int _i = 0; _i < 2; ++_i) \
;         __builtin_amdgcn_global_load_lds((const unsigned*)((const char*)(gbase) + (voff)[_i]), (PG8_LAS unsigned*)(lds + (bufoff) + ldsw + _i * 8192), 16, 0, 0); } while (0)
; #define PG8_LDA(dst, b, h) do { _Pragma("unroll") for (int m = 0; m < 4; ++m) _Pragma("unroll") for (int k = 0; k < 2; ++k) dst[m][k] = *(const PG8_LAS bf16x8*)(lds + PG8_SA(b, h) + aoff + m * 2048 + k * 1024); } while (0)
; #define PG8_LDB(dst, b, h) do { _Pragma("unroll") for (int n = 0; n < 2; ++n) _Pragma("unroll") for (int k = 0; k < 2; ++k) dst[n][k] = *(const PG8_LAS bf16x8*)(lds + PG8_SB(b, h) + boff + n * 2048 + k * 1024); } while (0)
; #define PG8_MMA(ai, bj, At, Bt) do { __builtin_amdgcn_s_setprio(1); _Pragma("unroll") for (int m = 0; m < 4; ++m) _Pragma("unroll") for (int n = 0; n < 2; ++n) _Pragma("unroll") for (int k = 0; k < 2; ++k) \
;         acc[ai][bj][m][n] = __builtin_amdgcn_mfma_f32_16x16x32_bf16(Bt[n][k], At[m][k], acc[ai][bj][m][n], 0, 0, 0); __builtin_amdgcn_s_setprio(0); } while (0)
; #define PG8_WAIT_V(n) asm volatile("s_waitcnt vmcnt(" #n ")" ::: "memory")
; #define PG8_WAIT_L(n) asm volatile("s_waitcnt lgkmcnt(" #n ")" ::: "memory")
; #define PG8_BAR __builtin_amdgcn_s_barrier()
; #define PG8_SCHED __builtin_amdgcn_sched_barrier(0)
; template <class Epi, class Sched, bool ALIGN_EPI = false, bool SP2 = false>
; __device__ __forceinline__ void gemm_phase(PG8_LAS unsigned char* lds, const Gemm g, const Sched& S, const Epi& E) {
;     ...
;             PG8_WAIT_V(8); PG8_WAIT_L(0); PG8_BAR; PG8_MMA(1, 0, At, B0); PG8_MMA(1, 1, At, B1); PG8_BAR; PG8_SCHED;
;             PG8_LDB(B0, 1, 0); PG8_LDB(B1, 1, 1); PG8_SCHED; PG8_LDA(At, 1, 0); PG8_STAGE(PG8_SA(0, 1), a2 + hstep, voffA);
;             PG8_WAIT_V(8); PG8_WAIT_L(0); PG8_BAR; PG8_MMA(0, 0, At, B0); PG8_MMA(0, 1, At, B1); PG8_BAR; PG8_SCHED;
	s_setprio 1
	v_mfma_f32_16x16x32_bf16 v[58:61], v[130:133], v[174:177], v[58:61]
	v_mfma_f32_16x16x32_bf16 v[54:57], v[138:141], v[174:177], v[54:57]
	v_mfma_f32_16x16x32_bf16 v[42:45], v[130:133], v[188:191], v[42:45]
	v_mfma_f32_16x16x32_bf16 v[38:41], v[138:141], v[188:191], v[38:41]
	v_mfma_f32_16x16x32_bf16 v[26:29], v[130:133], v[196:199], v[26:29]
	v_mfma_f32_16x16x32_bf16 v[22:25], v[138:141], v[196:199], v[22:25]
	v_mfma_f32_16x16x32_bf16 v[10:13], v[130:133], v[204:207], v[10:13]
	v_mfma_f32_16x16x32_bf16 v[6:9], v[138:141], v[204:207], v[6:9]
	v_mfma_f32_16x16x32_bf16 v[58:61], v[134:137], v[184:187], v[58:61]
	v_mfma_f32_16x16x32_bf16 v[54:57], v[142:145], v[184:187], v[54:57]
	v_mfma_f32_16x16x32_bf16 v[42:45], v[134:137], v[192:195], v[42:45]
	v_mfma_f32_16x16x32_bf16 v[38:41], v[142:145], v[192:195], v[38:41]
	v_mfma_f32_16x16x32_bf16 v[26:29], v[134:137], v[200:203], v[26:29]
	v_mfma_f32_16x16x32_bf16 v[22:25], v[142:145], v[200:203], v[22:25]
	v_mfma_f32_16x16x32_bf16 v[10:13], v[134:137], v[208:211], v[10:13]
	v_mfma_f32_16x16x32_bf16 v[6:9], v[142:145], v[208:211], v[6:9]
	v_mfma_f32_16x16x32_bf16 v[62:65], v[146:149], v[174:177], v[62:65]
	v_mfma_f32_16x16x32_bf16 v[50:53], v[166:169], v[174:177], v[50:53]
	v_mfma_f32_16x16x32_bf16 v[46:49], v[146:149], v[188:191], v[46:49]
	v_mfma_f32_16x16x32_bf16 v[34:37], v[166:169], v[188:191], v[34:37]
	v_mfma_f32_16x16x32_bf16 v[30:33], v[146:149], v[196:199], v[30:33]
	v_mfma_f32_16x16x32_bf16 v[18:21], v[166:169], v[196:199], v[18:21]
	v_mfma_f32_16x16x32_bf16 v[14:17], v[146:149], v[204:207], v[14:17]
	v_mfma_f32_16x16x32_bf16 v[2:5], v[166:169], v[204:207], v[2:5]
	v_mfma_f32_16x16x32_bf16 v[62:65], v[150:153], v[184:187], v[62:65]
	v_mfma_f32_16x16x32_bf16 v[50:53], v[170:173], v[184:187], v[50:53]
	v_mfma_f32_16x16x32_bf16 v[46:49], v[150:153], v[192:195], v[46:49]
	v_mfma_f32_16x16x32_bf16 v[34:37], v[170:173], v[192:195], v[34:37]
	v_mfma_f32_16x16x32_bf16 v[30:33], v[150:153], v[200:203], v[30:33]
	v_mfma_f32_16x16x32_bf16 v[18:21], v[170:173], v[200:203], v[18:21]
	v_mfma_f32_16x16x32_bf16 v[14:17], v[150:153], v[208:211], v[14:17]
	v_mfma_f32_16x16x32_bf16 v[2:5], v[170:173], v[208:211], v[2:5]
	s_setprio 0
	s_barrier
	ds_read_b128 v[130:133], v181 offset:32768
	ds_read_b128 v[134:137], v181 offset:33792
	ds_read_b128 v[138:141], v181 offset:34816
	ds_read_b128 v[142:145], v181 offset:35840
	ds_read_b128 v[146:149], v181 offset:49152
	ds_read_b128 v[150:153], v181 offset:50176
	ds_read_b128 v[166:169], v181 offset:51200
	ds_read_b128 v[170:173], v181 offset:52224
	s_add_u32 s20, s20, s10
	s_addc_u32 s21, s21, s11
	s_mov_b32 m0, s57
	v_lshl_add_u64 v[224:225], s[20:21], 0, v[158:159]
	ds_read_b128 v[174:177], v183 offset:32768
	ds_read_b128 v[184:187], v183 offset:33792
	ds_read_b128 v[188:191], v183 offset:34816
	ds_read_b128 v[192:195], v183 offset:35840
	ds_read_b128 v[196:199], v183 offset:36864
	ds_read_b128 v[200:203], v183 offset:37888
	ds_read_b128 v[204:207], v183 offset:38912
	ds_read_b128 v[208:211], v183 offset:39936
	global_load_lds_dwordx4 v[224:225], off
	s_mov_b32 m0, s58
	v_lshl_add_u64 v[224:225], s[20:21], 0, v[156:157]
	global_load_lds_dwordx4 v[224:225], off
	s_waitcnt vmcnt(8)
	s_waitcnt lgkmcnt(0)
	s_barrier
	s_setprio 1
	v_mfma_f32_16x16x32_bf16 v[122:125], v[130:133], v[174:177], v[122:125]
	v_mfma_f32_16x16x32_bf16 v[118:121], v[138:141], v[174:177], v[118:121]
	v_mfma_f32_16x16x32_bf16 v[106:109], v[130:133], v[188:191], v[106:109]
	v_mfma_f32_16x16x32_bf16 v[102:105], v[138:141], v[188:191], v[102:105]
	v_mfma_f32_16x16x32_bf16 v[90:93], v[130:133], v[196:199], v[90:93]
	v_mfma_f32_16x16x32_bf16 v[86:89], v[138:141], v[196:199], v[86:89]
	v_mfma_f32_16x16x32_bf16 v[74:77], v[130:133], v[204:207], v[74:77]
	v_mfma_f32_16x16x32_bf16 v[70:73], v[138:141], v[204:207], v[70:73]
	v_mfma_f32_16x16x32_bf16 v[122:125], v[134:137], v[184:187], v[122:125]
	v_mfma_f32_16x16x32_bf16 v[118:121], v[142:145], v[184:187], v[118:121]
	v_mfma_f32_16x16x32_bf16 v[106:109], v[134:137], v[192:195], v[106:109]
	v_mfma_f32_16x16x32_bf16 v[102:105], v[142:145], v[192:195], v[102:105]
	v_mfma_f32_16x16x32_bf16 v[90:93], v[134:137], v[200:203], v[90:93]
	v_mfma_f32_16x16x32_bf16 v[86:89], v[142:145], v[200:203], v[86:89]
	v_mfma_f32_16x16x32_bf16 v[74:77], v[134:137], v[208:211], v[74:77]
	v_mfma_f32_16x16x32_bf16 v[70:73], v[142:145], v[208:211], v[70:73]
	v_mfma_f32_16x16x32_bf16 v[126:129], v[146:149], v[174:177], v[126:129]
	v_mfma_f32_16x16x32_bf16 v[114:117], v[166:169], v[174:177], v[114:117]
	v_mfma_f32_16x16x32_bf16 v[110:113], v[146:149], v[188:191], v[110:113]
	v_mfma_f32_16x16x32_bf16 v[98:101], v[166:169], v[188:191], v[98:101]
	v_mfma_f32_16x16x32_bf16 v[94:97], v[146:149], v[196:199], v[94:97]
	v_mfma_f32_16x16x32_bf16 v[82:85], v[166:169], v[196:199], v[82:85]
	v_mfma_f32_16x16x32_bf16 v[78:81], v[146:149], v[204:207], v[78:81]
	v_mfma_f32_16x16x32_bf16 v[66:69], v[166:169], v[204:207], v[66:69]
	v_mfma_f32_16x16x32_bf16 v[126:129], v[150:153], v[184:187], v[126:129]
	v_mfma_f32_16x16x32_bf16 v[114:117], v[170:173], v[184:187], v[114:117]
	v_mfma_f32_16x16x32_bf16 v[110:113], v[150:153], v[192:195], v[110:113]
	v_mfma_f32_16x16x32_bf16 v[98:101], v[170:173], v[192:195], v[98:101]
	v_mfma_f32_16x16x32_bf16 v[94:97], v[150:153], v[200:203], v[94:97]
	v_mfma_f32_16x16x32_bf16 v[82:85], v[170:173], v[200:203], v[82:85]
	v_mfma_f32_16x16x32_bf16 v[78:81], v[150:153], v[208:211], v[78:81]
	v_mfma_f32_16x16x32_bf16 v[66:69], v[170:173], v[208:211], v[66:69]
	s_setprio 0
	s_barrier
; #define PG8_STAGE(bufoff, gbase, voff) do { _Pragma("unroll") for (int _i = 0; _i < 2; ++_i) \
;         __builtin_amdgcn_global_load_lds((const unsigned*)((const char*)(gbase) + (voff)[_i]), (PG8_LAS unsigned*)(lds + (bufoff) + ldsw + _i * 8192), 16, 0, 0); } while (0)
; #define PG8_LDA(dst, b, h) do { _Pragma("unroll") for (int m = 0; m < 4; ++m) _Pragma("unroll") for (int k = 0; k < 2; ++k) dst[m][k] = *(const PG8_LAS bf16x8*)(lds + PG8_SA(b, h) + aoff + m * 2048 + k * 1024); } while (0)
; #define PG8_MMA(ai, bj, At, Bt) do { __builtin_amdgcn_s_setprio(1); _Pragma("unroll") for (int m = 0; m < 4; ++m) _Pragma("unroll") for (int n = 0; n < 2; ++n) _Pragma("unroll") for (int k = 0; k < 2; ++k) \
;         acc[ai][bj][m][n] = __builtin_amdgcn_mfma_f32_16x16x32_bf16(Bt[n][k], At[m][k], acc[ai][bj][m][n], 0, 0, 0); __builtin_amdgcn_s_setprio(0); } while (0)
; #define PG8_WAIT_V(n) asm volatile("s_waitcnt vmcnt(" #n ")" ::: "memory")
; #define PG8_WAIT_L(n) asm volatile("s_waitcnt lgkmcnt(" #n ")" ::: "memory")
; #define PG8_BAR __builtin_amdgcn_s_barrier()
; #define PG8_SCHED __builtin_amdgcn_sched_barrier(0)
; template <class Epi, class Sched, bool ALIGN_EPI = false, bool SP2 = false>
; __device__ __forceinline__ void gemm_phase(PG8_LAS unsigned char* lds, const Gemm g, const Sched& S, const Epi& E) {
;     ...
;         for (int t = 0; t < nt; t += 2) {
;             const bool last = (t == nt - 2);
;             const char* a1 = cA + (size_t)(t + 1) * kstep;
;             const char* a2 = last ? nA : cA + (size_t)(t + 2) * kstep; const char* b2 = last ? nB : cB + (size_t)(t + 2) * kstep;
;             const char* a3 = a2 + kstep; const char* b3 = b2 + kstep;
;     ...
;             PG8_LDA(At, 1, 1); PG8_STAGE(PG8_SB(1, 0), b3, voffB); PG8_STAGE(PG8_SB(1, 1), b3 + hstep, voffB); PG8_STAGE(PG8_SA(1, 0), a3, voffA);
;             PG8_WAIT_V(8); PG8_WAIT_L(0); PG8_BAR; PG8_MMA(1, 0, At, B0); PG8_MMA(1, 1, At, B1); PG8_BAR; PG8_SCHED;
	s_add_i32 m0, s23, 0x17f80
	ds_read_b128 v[174:177], v183 offset:49152
	ds_read_b128 v[184:187], v183 offset:50176
	ds_read_b128 v[188:191], v183 offset:51200
	global_load_lds_dwordx4 v[178:179], off offset:128
	s_add_i32 m0, s23, 0x19f80
	ds_read_b128 v[192:195], v183 offset:52224
	global_load_lds_dwordx4 v[212:213], off offset:128
	s_add_i32 m0, s23, 0x1bf80
	ds_read_b128 v[196:199], v183 offset:53248
	global_load_lds_dwordx4 v[214:215], off offset:128
	s_add_i32 m0, s23, 0x1df80
	ds_read_b128 v[200:203], v183 offset:54272
	global_load_lds_dwordx4 v[218:219], off offset:128
	s_sub_i32 m0, s59, 0x80
	ds_read_b128 v[204:207], v183 offset:55296
	global_load_lds_dwordx4 v[220:221], off offset:128
	s_sub_i32 m0, s60, 0x80
	ds_read_b128 v[208:211], v183 offset:56320
	global_load_lds_dwordx4 v[222:223], off offset:128
	s_waitcnt vmcnt(8)
	s_waitcnt lgkmcnt(0)
	s_barrier
	s_setprio 1
	v_mfma_f32_16x16x32_bf16 v[58:61], v[130:133], v[174:177], v[58:61]
	v_mfma_f32_16x16x32_bf16 v[54:57], v[138:141], v[174:177], v[54:57]
	v_mfma_f32_16x16x32_bf16 v[42:45], v[130:133], v[188:191], v[42:45]
	v_mfma_f32_16x16x32_bf16 v[38:41], v[138:141], v[188:191], v[38:41]
	v_mfma_f32_16x16x32_bf16 v[26:29], v[130:133], v[196:199], v[26:29]
	v_mfma_f32_16x16x32_bf16 v[22:25], v[138:141], v[196:199], v[22:25]
	v_mfma_f32_16x16x32_bf16 v[10:13], v[130:133], v[204:207], v[10:13]
	v_mfma_f32_16x16x32_bf16 v[6:9], v[138:141], v[204:207], v[6:9]
	v_mfma_f32_16x16x32_bf16 v[58:61], v[134:137], v[184:187], v[58:61]
	v_mfma_f32_16x16x32_bf16 v[54:57], v[142:145], v[184:187], v[54:57]
	v_mfma_f32_16x16x32_bf16 v[42:45], v[134:137], v[192:195], v[42:45]
	v_mfma_f32_16x16x32_bf16 v[38:41], v[142:145], v[192:195], v[38:41]
	v_mfma_f32_16x16x32_bf16 v[26:29], v[134:137], v[200:203], v[26:29]
	v_mfma_f32_16x16x32_bf16 v[22:25], v[142:145], v[200:203], v[22:25]
	v_mfma_f32_16x16x32_bf16 v[10:13], v[134:137], v[208:211], v[10:13]
	v_mfma_f32_16x16x32_bf16 v[6:9], v[142:145], v[208:211], v[6:9]
	v_mfma_f32_16x16x32_bf16 v[62:65], v[146:149], v[174:177], v[62:65]
	v_mfma_f32_16x16x32_bf16 v[50:53], v[166:169], v[174:177], v[50:53]
	v_mfma_f32_16x16x32_bf16 v[46:49], v[146:149], v[188:191], v[46:49]
	v_mfma_f32_16x16x32_bf16 v[34:37], v[166:169], v[188:191], v[34:37]
	v_mfma_f32_16x16x32_bf16 v[30:33], v[146:149], v[196:199], v[30:33]
	v_mfma_f32_16x16x32_bf16 v[18:21], v[166:169], v[196:199], v[18:21]
	v_mfma_f32_16x16x32_bf16 v[14:17], v[146:149], v[204:207], v[14:17]
	v_mfma_f32_16x16x32_bf16 v[2:5], v[166:169], v[204:207], v[2:5]
	v_mfma_f32_16x16x32_bf16 v[62:65], v[150:153], v[184:187], v[62:65]
	v_mfma_f32_16x16x32_bf16 v[50:53], v[170:173], v[184:187], v[50:53]
	v_mfma_f32_16x16x32_bf16 v[46:49], v[150:153], v[192:195], v[46:49]
	v_mfma_f32_16x16x32_bf16 v[34:37], v[170:173], v[192:195], v[34:37]
	v_mfma_f32_16x16x32_bf16 v[30:33], v[150:153], v[200:203], v[30:33]
	v_mfma_f32_16x16x32_bf16 v[18:21], v[170:173], v[200:203], v[18:21]
	v_mfma_f32_16x16x32_bf16 v[14:17], v[150:153], v[208:211], v[14:17]
	v_mfma_f32_16x16x32_bf16 v[2:5], v[170:173], v[208:211], v[2:5]
	s_setprio 0
	s_barrier
	s_add_u32 s8, s8, 0x100
	s_addc_u32 s9, s9, 0
	s_add_u32 s52, s52, 0x100
	s_addc_u32 s53, s53, 0
	s_cmp_ge_i32 s68, s62
	s_mov_b32 s20, s68
	s_cbranch_scc0 .LBB0_641
